# FFN-up GEMM tile order: supergroup height WGM 2->4 (4 M-rows x 8 N-cols per XCD round) for L2 panel reuse, on top of v14
# speedup vs baseline: 1.0140x; 1.0091x over previous
;     __device__ __forceinline__ bool next(int i, Unit& u) const {
;         const long L = (long)i * G + c; if (L >= nwg) return false;
;         int wgid = (int)L; { const int q = nwg / NXCD, r = nwg % NXCD, xcd = wgid % NXCD, off = wgid / NXCD; wgid = (xcd < r ? xcd * (q + 1) : r * (q + 1) + (xcd - r) * q) + off; }
;         const int nig = WGM * nN, gid = wgid / nig, fm = gid * WGM, gsz = (nM - fm) < WGM ? (nM - fm) : WGM;
;         u.pm = fm + ((wgid % nig) % gsz); u.pn = (wgid % nig) / gsz; u.idx = i; return true;
;     }
; __global__ void __launch_bounds__(512, 2) hybrid_fwd(Args args) {
;     ...
;         { pg8::Unit pu; for (int i = 0; S.next(i, pu); ++i) if (tid < 256) rst[i * 256 + tid] = row_rstd(SSQ + SSQ_STRIDE, pu.pm * 256 + tid);
.LBB0_576:
	s_cmp_lt_i32 s82, 6
	s_cselect_b64 s[8:9], -1, 0
	s_and_b64 s[18:19], s[8:9], s[6:7]
	s_andn2_b64 vcc, exec, s[18:19]
	s_cbranch_vccnz .LBB0_636
	v_mov_b32_e32 v4, v220
	s_load_dword s52, s[0:1], 0xb0
	s_waitcnt lgkmcnt(0)
	s_ashr_i32 s3, s2, 31
	s_movk_i32 s6, 0x100
	v_lshl_add_u32 v0, v4, 2, 0
	v_cmp_gt_i32_e64 s[6:7], s6, v4
	s_ashr_i32 s53, s52, 31
	s_add_u32 s8, s80, 0x3600000
	s_addc_u32 s9, s81, 0
	v_add_u32_e32 v5, 0x22000, v0
	v_mov_b64_e32 v[0:1], 0xb00
	v_mov_b64_e32 v[2:3], 0xaff
	s_movk_i32 s14, 0x161
	v_mov_b32_e32 v6, 0x358637bd
	s_mov_b32 s15, 0x800000
	s_mov_b64 s[10:11], s[2:3]
	s_cmp_lg_u32 s52, 0x100
	s_cbranch_scc1 .Lrs1_slow
	s_ashr_i32 s12, s10, 31
	s_lshr_b32 s12, s12, 29
	s_add_i32 s12, s10, s12
	s_ashr_i32 s13, s12, 3
	s_and_b32 s12, s12, -8
	s_sub_i32 s12, s10, s12
	s_cmp_lt_i32 s12, 0
	s_cselect_b32 s16, s14, 0x160
	s_mul_i32 s12, s12, s16
	s_add_i32 s12, s12, s13
	s_mul_hi_i32 s13, s12, 0x2e8ba2e9
	s_lshr_b32 s16, s13, 31
	s_ashr_i32 s13, s13, 4
	s_add_i32 s13, s13, s16
	s_lshl_b32 s16, s13, 2
	s_sub_i32 s17, 0x80, s16
	s_min_i32 s17, s17, 4
	s_abs_i32 s17, s17
	v_cvt_f32_u32_e32 v7, s17
	s_sub_i32 s20, 0, s17
	s_mul_i32 s13, s13, 88
	s_sub_i32 s12, s12, s13
	v_rcp_iflag_f32_e32 v7, v7
	s_ashr_i32 s13, s12, 31
	s_abs_i32 s12, s12
	v_mul_f32_e32 v7, 0x4f7ffffe, v7
	v_cvt_u32_f32_e32 v7, v7
	s_nop 0
	v_readfirstlane_b32 s21, v7
	s_mul_i32 s20, s20, s21
	s_mul_hi_u32 s20, s21, s20
	s_add_i32 s21, s21, s20
	s_mul_hi_u32 s20, s12, s21
	s_mul_i32 s20, s20, s17
	s_sub_i32 s12, s12, s20
	s_sub_i32 s20, s12, s17
	s_cmp_ge_u32 s12, s17
	s_cselect_b32 s12, s20, s12
	s_sub_i32 s20, s12, s17
	s_cmp_ge_u32 s12, s17
	s_cselect_b32 s12, s20, s12
	s_xor_b32 s12, s12, s13
	s_sub_i32 s12, s12, s13
	s_add_i32 s16, s16, s12
	s_and_saveexec_b64 s[12:13], s[6:7]
	v_lshl_add_u32 v32, s16, 8, v4
	v_ashrrev_i32_e32 v33, 31, v32
	v_lshlrev_b64 v[32:33], 6, v[32:33]
	v_lshl_add_u64 v[24:25], s[8:9], 0, v[32:33]
	global_load_dwordx4 v[32:35], v[24:25], off
	global_load_dwordx4 v[36:39], v[24:25], off offset:16
	global_load_dwordx4 v[40:43], v[24:25], off offset:32
	global_load_dwordx4 v[44:47], v[24:25], off offset:48
	s_or_b64 exec, exec, s[12:13]
	s_add_u32 s10, s10, s52
	s_addc_u32 s11, s11, s53
	s_ashr_i32 s12, s10, 31
	s_lshr_b32 s12, s12, 29
	s_add_i32 s12, s10, s12
	s_ashr_i32 s13, s12, 3
	s_and_b32 s12, s12, -8
	s_sub_i32 s12, s10, s12
	s_cmp_lt_i32 s12, 0
	s_cselect_b32 s16, s14, 0x160
	s_mul_i32 s12, s12, s16
	s_add_i32 s12, s12, s13
	s_mul_hi_i32 s13, s12, 0x2e8ba2e9
	s_lshr_b32 s16, s13, 31
	s_ashr_i32 s13, s13, 4
	s_add_i32 s13, s13, s16
	s_lshl_b32 s16, s13, 2
	s_sub_i32 s17, 0x80, s16
	s_min_i32 s17, s17, 4
	s_abs_i32 s17, s17
	v_cvt_f32_u32_e32 v7, s17
	s_sub_i32 s20, 0, s17
	s_mul_i32 s13, s13, 88
	s_sub_i32 s12, s12, s13
	v_rcp_iflag_f32_e32 v7, v7
	s_ashr_i32 s13, s12, 31
	s_abs_i32 s12, s12
	v_mul_f32_e32 v7, 0x4f7ffffe, v7
	v_cvt_u32_f32_e32 v7, v7
	s_nop 0
	v_readfirstlane_b32 s21, v7
	s_mul_i32 s20, s20, s21
	s_mul_hi_u32 s20, s21, s20
	s_add_i32 s21, s21, s20
	s_mul_hi_u32 s20, s12, s21
	s_mul_i32 s20, s20, s17
	s_sub_i32 s12, s12, s20
	s_sub_i32 s20, s12, s17
	s_cmp_ge_u32 s12, s17
	s_cselect_b32 s12, s20, s12
	s_sub_i32 s20, s12, s17
	s_cmp_ge_u32 s12, s17
	s_cselect_b32 s12, s20, s12
	s_xor_b32 s12, s12, s13
	s_sub_i32 s12, s12, s13
	s_add_i32 s16, s16, s12
	s_and_saveexec_b64 s[12:13], s[6:7]
	v_lshl_add_u32 v48, s16, 8, v4
	v_ashrrev_i32_e32 v49, 31, v48
	v_lshlrev_b64 v[48:49], 6, v[48:49]
	v_lshl_add_u64 v[24:25], s[8:9], 0, v[48:49]
	global_load_dwordx4 v[48:51], v[24:25], off
	global_load_dwordx4 v[52:55], v[24:25], off offset:16
	global_load_dwordx4 v[56:59], v[24:25], off offset:32
	global_load_dwordx4 v[60:63], v[24:25], off offset:48
	s_or_b64 exec, exec, s[12:13]
	s_add_u32 s10, s10, s52
	s_addc_u32 s11, s11, s53
	s_ashr_i32 s12, s10, 31
	s_lshr_b32 s12, s12, 29
	s_add_i32 s12, s10, s12
	s_ashr_i32 s13, s12, 3
	s_and_b32 s12, s12, -8
	s_sub_i32 s12, s10, s12
	s_cmp_lt_i32 s12, 0
	s_cselect_b32 s16, s14, 0x160
	s_mul_i32 s12, s12, s16
	s_add_i32 s12, s12, s13
	s_mul_hi_i32 s13, s12, 0x2e8ba2e9
	s_lshr_b32 s16, s13, 31
	s_ashr_i32 s13, s13, 4
	s_add_i32 s13, s13, s16
	s_lshl_b32 s16, s13, 2
	s_sub_i32 s17, 0x80, s16
	s_min_i32 s17, s17, 4
	s_abs_i32 s17, s17
	v_cvt_f32_u32_e32 v7, s17
	s_sub_i32 s20, 0, s17
	s_mul_i32 s13, s13, 88
	s_sub_i32 s12, s12, s13
	v_rcp_iflag_f32_e32 v7, v7
	s_ashr_i32 s13, s12, 31
	s_abs_i32 s12, s12
	v_mul_f32_e32 v7, 0x4f7ffffe, v7
	v_cvt_u32_f32_e32 v7, v7
	s_nop 0
	v_readfirstlane_b32 s21, v7
	s_mul_i32 s20, s20, s21
	s_mul_hi_u32 s20, s21, s20
	s_add_i32 s21, s21, s20
	s_mul_hi_u32 s20, s12, s21
	s_mul_i32 s20, s20, s17
	s_sub_i32 s12, s12, s20
	s_sub_i32 s20, s12, s17
	s_cmp_ge_u32 s12, s17
	s_cselect_b32 s12, s20, s12
	s_sub_i32 s20, s12, s17
	s_cmp_ge_u32 s12, s17
	s_cselect_b32 s12, s20, s12
	s_xor_b32 s12, s12, s13
	s_sub_i32 s12, s12, s13
	s_add_i32 s16, s16, s12
	s_and_saveexec_b64 s[12:13], s[6:7]
	v_lshl_add_u32 v64, s16, 8, v4
	v_ashrrev_i32_e32 v65, 31, v64
	v_lshlrev_b64 v[64:65], 6, v[64:65]
	v_lshl_add_u64 v[24:25], s[8:9], 0, v[64:65]
	global_load_dwordx4 v[64:67], v[24:25], off
	global_load_dwordx4 v[68:71], v[24:25], off offset:16
	global_load_dwordx4 v[72:75], v[24:25], off offset:32
	global_load_dwordx4 v[76:79], v[24:25], off offset:48
	s_or_b64 exec, exec, s[12:13]
	s_add_u32 s10, s10, s52
	s_addc_u32 s11, s11, s53
	s_ashr_i32 s12, s10, 31
	s_lshr_b32 s12, s12, 29
	s_add_i32 s12, s10, s12
	s_ashr_i32 s13, s12, 3
	s_and_b32 s12, s12, -8
	s_sub_i32 s12, s10, s12
	s_cmp_lt_i32 s12, 0
	s_cselect_b32 s16, s14, 0x160
	s_mul_i32 s12, s12, s16
;     __device__ __forceinline__ bool next(int i, Unit& u) const {
;         const long L = (long)i * G + c; if (L >= nwg) return false;
;         int wgid = (int)L; { const int q = nwg / NXCD, r = nwg % NXCD, xcd = wgid % NXCD, off = wgid / NXCD; wgid = (xcd < r ? xcd * (q + 1) : r * (q + 1) + (xcd - r) * q) + off; }
;         const int nig = WGM * nN, gid = wgid / nig, fm = gid * WGM, gsz = (nM - fm) < WGM ? (nM - fm) : WGM;
;         u.pm = fm + ((wgid % nig) % gsz); u.pn = (wgid % nig) / gsz; u.idx = i; return true;
;     }
; __global__ void __launch_bounds__(512, 2) hybrid_fwd(Args args) {
;     ...
;         { pg8::Unit pu; for (int i = 0; S.next(i, pu); ++i) if (tid < 256) rst[i * 256 + tid] = row_rstd(SSQ + SSQ_STRIDE, pu.pm * 256 + tid);
	s_add_i32 s12, s12, s13
	s_mul_hi_i32 s13, s12, 0x2e8ba2e9
	s_lshr_b32 s16, s13, 31
	s_ashr_i32 s13, s13, 4
	s_add_i32 s13, s13, s16
	s_lshl_b32 s16, s13, 2
	s_sub_i32 s17, 0x80, s16
	s_min_i32 s17, s17, 4
	s_abs_i32 s17, s17
	v_cvt_f32_u32_e32 v7, s17
	s_sub_i32 s20, 0, s17
	s_mul_i32 s13, s13, 88
	s_sub_i32 s12, s12, s13
	v_rcp_iflag_f32_e32 v7, v7
	s_ashr_i32 s13, s12, 31
	s_abs_i32 s12, s12
	v_mul_f32_e32 v7, 0x4f7ffffe, v7
	v_cvt_u32_f32_e32 v7, v7
	s_nop 0
	v_readfirstlane_b32 s21, v7
	s_mul_i32 s20, s20, s21
	s_mul_hi_u32 s20, s21, s20
	s_add_i32 s21, s21, s20
	s_mul_hi_u32 s20, s12, s21
	s_mul_i32 s20, s20, s17
	s_sub_i32 s12, s12, s20
	s_sub_i32 s20, s12, s17
	s_cmp_ge_u32 s12, s17
	s_cselect_b32 s12, s20, s12
	s_sub_i32 s20, s12, s17
	s_cmp_ge_u32 s12, s17
	s_cselect_b32 s12, s20, s12
	s_xor_b32 s12, s12, s13
	s_sub_i32 s12, s12, s13
	s_add_i32 s16, s16, s12
	s_and_saveexec_b64 s[12:13], s[6:7]
	v_lshl_add_u32 v80, s16, 8, v4
	v_ashrrev_i32_e32 v81, 31, v80
	v_lshlrev_b64 v[80:81], 6, v[80:81]
	v_lshl_add_u64 v[24:25], s[8:9], 0, v[80:81]
	global_load_dwordx4 v[80:83], v[24:25], off
	global_load_dwordx4 v[84:87], v[24:25], off offset:16
	global_load_dwordx4 v[88:91], v[24:25], off offset:32
	global_load_dwordx4 v[92:95], v[24:25], off offset:48
	s_or_b64 exec, exec, s[12:13]
	s_add_u32 s10, s10, s52
	s_addc_u32 s11, s11, s53
	s_ashr_i32 s12, s10, 31
	s_lshr_b32 s12, s12, 29
	s_add_i32 s12, s10, s12
	s_ashr_i32 s13, s12, 3
	s_and_b32 s12, s12, -8
	s_sub_i32 s12, s10, s12
	s_cmp_lt_i32 s12, 0
	s_cselect_b32 s16, s14, 0x160
	s_mul_i32 s12, s12, s16
	s_add_i32 s12, s12, s13
	s_mul_hi_i32 s13, s12, 0x2e8ba2e9
	s_lshr_b32 s16, s13, 31
	s_ashr_i32 s13, s13, 4
	s_add_i32 s13, s13, s16
	s_lshl_b32 s16, s13, 2
	s_sub_i32 s17, 0x80, s16
	s_min_i32 s17, s17, 4
	s_abs_i32 s17, s17
	v_cvt_f32_u32_e32 v7, s17
	s_sub_i32 s20, 0, s17
	s_mul_i32 s13, s13, 88
	s_sub_i32 s12, s12, s13
	v_rcp_iflag_f32_e32 v7, v7
	s_ashr_i32 s13, s12, 31
	s_abs_i32 s12, s12
	v_mul_f32_e32 v7, 0x4f7ffffe, v7
	v_cvt_u32_f32_e32 v7, v7
	s_nop 0
	v_readfirstlane_b32 s21, v7
	s_mul_i32 s20, s20, s21
	s_mul_hi_u32 s20, s21, s20
	s_add_i32 s21, s21, s20
	s_mul_hi_u32 s20, s12, s21
	s_mul_i32 s20, s20, s17
	s_sub_i32 s12, s12, s20
	s_sub_i32 s20, s12, s17
	s_cmp_ge_u32 s12, s17
	s_cselect_b32 s12, s20, s12
	s_sub_i32 s20, s12, s17
	s_cmp_ge_u32 s12, s17
	s_cselect_b32 s12, s20, s12
	s_xor_b32 s12, s12, s13
	s_sub_i32 s12, s12, s13
	s_add_i32 s16, s16, s12
	s_and_saveexec_b64 s[12:13], s[6:7]
	v_lshl_add_u32 v96, s16, 8, v4
	v_ashrrev_i32_e32 v97, 31, v96
	v_lshlrev_b64 v[96:97], 6, v[96:97]
	v_lshl_add_u64 v[24:25], s[8:9], 0, v[96:97]
	global_load_dwordx4 v[96:99], v[24:25], off
	global_load_dwordx4 v[100:103], v[24:25], off offset:16
	global_load_dwordx4 v[104:107], v[24:25], off offset:32
	global_load_dwordx4 v[108:111], v[24:25], off offset:48
	s_or_b64 exec, exec, s[12:13]
	s_add_u32 s10, s10, s52
	s_addc_u32 s11, s11, s53
	s_ashr_i32 s12, s10, 31
	s_lshr_b32 s12, s12, 29
	s_add_i32 s12, s10, s12
	s_ashr_i32 s13, s12, 3
	s_and_b32 s12, s12, -8
	s_sub_i32 s12, s10, s12
	s_cmp_lt_i32 s12, 0
	s_cselect_b32 s16, s14, 0x160
	s_mul_i32 s12, s12, s16
	s_add_i32 s12, s12, s13
	s_mul_hi_i32 s13, s12, 0x2e8ba2e9
	s_lshr_b32 s16, s13, 31
	s_ashr_i32 s13, s13, 4
	s_add_i32 s13, s13, s16
	s_lshl_b32 s16, s13, 2
	s_sub_i32 s17, 0x80, s16
	s_min_i32 s17, s17, 4
	s_abs_i32 s17, s17
	v_cvt_f32_u32_e32 v7, s17
	s_sub_i32 s20, 0, s17
	s_mul_i32 s13, s13, 88
	s_sub_i32 s12, s12, s13
	v_rcp_iflag_f32_e32 v7, v7
	s_ashr_i32 s13, s12, 31
	s_abs_i32 s12, s12
	v_mul_f32_e32 v7, 0x4f7ffffe, v7
	v_cvt_u32_f32_e32 v7, v7
	s_nop 0
	v_readfirstlane_b32 s21, v7
	s_mul_i32 s20, s20, s21
	s_mul_hi_u32 s20, s21, s20
	s_add_i32 s21, s21, s20
	s_mul_hi_u32 s20, s12, s21
	s_mul_i32 s20, s20, s17
	s_sub_i32 s12, s12, s20
	s_sub_i32 s20, s12, s17
	s_cmp_ge_u32 s12, s17
	s_cselect_b32 s12, s20, s12
	s_sub_i32 s20, s12, s17
	s_cmp_ge_u32 s12, s17
	s_cselect_b32 s12, s20, s12
	s_xor_b32 s12, s12, s13
	s_sub_i32 s12, s12, s13
	s_add_i32 s16, s16, s12
	s_and_saveexec_b64 s[12:13], s[6:7]
	v_lshl_add_u32 v112, s16, 8, v4
	v_ashrrev_i32_e32 v113, 31, v112
	v_lshlrev_b64 v[112:113], 6, v[112:113]
	v_lshl_add_u64 v[24:25], s[8:9], 0, v[112:113]
	global_load_dwordx4 v[112:115], v[24:25], off
	global_load_dwordx4 v[116:119], v[24:25], off offset:16
	global_load_dwordx4 v[120:123], v[24:25], off offset:32
	global_load_dwordx4 v[124:127], v[24:25], off offset:48
	s_or_b64 exec, exec, s[12:13]
	s_add_u32 s10, s10, s52
	s_addc_u32 s11, s11, s53
	s_ashr_i32 s12, s10, 31
	s_lshr_b32 s12, s12, 29
	s_add_i32 s12, s10, s12
	s_ashr_i32 s13, s12, 3
	s_and_b32 s12, s12, -8
	s_sub_i32 s12, s10, s12
	s_cmp_lt_i32 s12, 0
	s_cselect_b32 s16, s14, 0x160
	s_mul_i32 s12, s12, s16
	s_add_i32 s12, s12, s13
	s_mul_hi_i32 s13, s12, 0x2e8ba2e9
	s_lshr_b32 s16, s13, 31
	s_ashr_i32 s13, s13, 4
	s_add_i32 s13, s13, s16
	s_lshl_b32 s16, s13, 2
	s_sub_i32 s17, 0x80, s16
	s_min_i32 s17, s17, 4
	s_abs_i32 s17, s17
	v_cvt_f32_u32_e32 v7, s17
	s_sub_i32 s20, 0, s17
	s_mul_i32 s13, s13, 88
	s_sub_i32 s12, s12, s13
	v_rcp_iflag_f32_e32 v7, v7
	s_ashr_i32 s13, s12, 31
	s_abs_i32 s12, s12
	v_mul_f32_e32 v7, 0x4f7ffffe, v7
	v_cvt_u32_f32_e32 v7, v7
	s_nop 0
	v_readfirstlane_b32 s21, v7
	s_mul_i32 s20, s20, s21
	s_mul_hi_u32 s20, s21, s20
	s_add_i32 s21, s21, s20
	s_mul_hi_u32 s20, s12, s21
	s_mul_i32 s20, s20, s17
	s_sub_i32 s12, s12, s20
	s_sub_i32 s20, s12, s17
	s_cmp_ge_u32 s12, s17
	s_cselect_b32 s12, s20, s12
	s_sub_i32 s20, s12, s17
	s_cmp_ge_u32 s12, s17
	s_cselect_b32 s12, s20, s12
	s_xor_b32 s12, s12, s13
	s_sub_i32 s12, s12, s13
;     __device__ __forceinline__ bool next(int i, Unit& u) const {
;         const long L = (long)i * G + c; if (L >= nwg) return false;
;         int wgid = (int)L; { const int q = nwg / NXCD, r = nwg % NXCD, xcd = wgid % NXCD, off = wgid / NXCD; wgid = (xcd < r ? xcd * (q + 1) : r * (q + 1) + (xcd - r) * q) + off; }
;         const int nig = WGM * nN, gid = wgid / nig, fm = gid * WGM, gsz = (nM - fm) < WGM ? (nM - fm) : WGM;
;         u.pm = fm + ((wgid % nig) % gsz); u.pn = (wgid % nig) / gsz; u.idx = i; return true;
;     }
; __global__ void __launch_bounds__(512, 2) hybrid_fwd(Args args) {
;     ...
;         { pg8::Unit pu; for (int i = 0; S.next(i, pu); ++i) if (tid < 256) rst[i * 256 + tid] = row_rstd(SSQ + SSQ_STRIDE, pu.pm * 256 + tid);
	s_add_i32 s16, s16, s12
	s_and_saveexec_b64 s[12:13], s[6:7]
	v_lshl_add_u32 v128, s16, 8, v4
	v_ashrrev_i32_e32 v129, 31, v128
	v_lshlrev_b64 v[128:129], 6, v[128:129]
	v_lshl_add_u64 v[24:25], s[8:9], 0, v[128:129]
	global_load_dwordx4 v[128:131], v[24:25], off
	global_load_dwordx4 v[132:135], v[24:25], off offset:16
	global_load_dwordx4 v[136:139], v[24:25], off offset:32
	global_load_dwordx4 v[140:143], v[24:25], off offset:48
	s_or_b64 exec, exec, s[12:13]
	s_add_u32 s10, s10, s52
	s_addc_u32 s11, s11, s53
	s_ashr_i32 s12, s10, 31
	s_lshr_b32 s12, s12, 29
	s_add_i32 s12, s10, s12
	s_ashr_i32 s13, s12, 3
	s_and_b32 s12, s12, -8
	s_sub_i32 s12, s10, s12
	s_cmp_lt_i32 s12, 0
	s_cselect_b32 s16, s14, 0x160
	s_mul_i32 s12, s12, s16
	s_add_i32 s12, s12, s13
	s_mul_hi_i32 s13, s12, 0x2e8ba2e9
	s_lshr_b32 s16, s13, 31
	s_ashr_i32 s13, s13, 4
	s_add_i32 s13, s13, s16
	s_lshl_b32 s16, s13, 2
	s_sub_i32 s17, 0x80, s16
	s_min_i32 s17, s17, 4
	s_abs_i32 s17, s17
	v_cvt_f32_u32_e32 v7, s17
	s_sub_i32 s20, 0, s17
	s_mul_i32 s13, s13, 88
	s_sub_i32 s12, s12, s13
	v_rcp_iflag_f32_e32 v7, v7
	s_ashr_i32 s13, s12, 31
	s_abs_i32 s12, s12
	v_mul_f32_e32 v7, 0x4f7ffffe, v7
	v_cvt_u32_f32_e32 v7, v7
	s_nop 0
	v_readfirstlane_b32 s21, v7
	s_mul_i32 s20, s20, s21
	s_mul_hi_u32 s20, s21, s20
	s_add_i32 s21, s21, s20
	s_mul_hi_u32 s20, s12, s21
	s_mul_i32 s20, s20, s17
	s_sub_i32 s12, s12, s20
	s_sub_i32 s20, s12, s17
	s_cmp_ge_u32 s12, s17
	s_cselect_b32 s12, s20, s12
	s_sub_i32 s20, s12, s17
	s_cmp_ge_u32 s12, s17
	s_cselect_b32 s12, s20, s12
	s_xor_b32 s12, s12, s13
	s_sub_i32 s12, s12, s13
	s_add_i32 s16, s16, s12
	s_and_saveexec_b64 s[12:13], s[6:7]
	v_lshl_add_u32 v144, s16, 8, v4
	v_ashrrev_i32_e32 v145, 31, v144
	v_lshlrev_b64 v[144:145], 6, v[144:145]
	v_lshl_add_u64 v[24:25], s[8:9], 0, v[144:145]
	global_load_dwordx4 v[144:147], v[24:25], off
	global_load_dwordx4 v[148:151], v[24:25], off offset:16
	global_load_dwordx4 v[152:155], v[24:25], off offset:32
	global_load_dwordx4 v[156:159], v[24:25], off offset:48
	s_or_b64 exec, exec, s[12:13]
	s_add_u32 s10, s10, s52
	s_addc_u32 s11, s11, s53
	s_ashr_i32 s12, s10, 31
	s_lshr_b32 s12, s12, 29
	s_add_i32 s12, s10, s12
	s_ashr_i32 s13, s12, 3
	s_and_b32 s12, s12, -8
	s_sub_i32 s12, s10, s12
	s_cmp_lt_i32 s12, 0
	s_cselect_b32 s16, s14, 0x160
	s_mul_i32 s12, s12, s16
	s_add_i32 s12, s12, s13
	s_mul_hi_i32 s13, s12, 0x2e8ba2e9
	s_lshr_b32 s16, s13, 31
	s_ashr_i32 s13, s13, 4
	s_add_i32 s13, s13, s16
	s_lshl_b32 s16, s13, 2
	s_sub_i32 s17, 0x80, s16
	s_min_i32 s17, s17, 4
	s_abs_i32 s17, s17
	v_cvt_f32_u32_e32 v7, s17
	s_sub_i32 s20, 0, s17
	s_mul_i32 s13, s13, 88
	s_sub_i32 s12, s12, s13
	v_rcp_iflag_f32_e32 v7, v7
	s_ashr_i32 s13, s12, 31
	s_abs_i32 s12, s12
	v_mul_f32_e32 v7, 0x4f7ffffe, v7
	v_cvt_u32_f32_e32 v7, v7
	s_nop 0
	v_readfirstlane_b32 s21, v7
	s_mul_i32 s20, s20, s21
	s_mul_hi_u32 s20, s21, s20
	s_add_i32 s21, s21, s20
	s_mul_hi_u32 s20, s12, s21
	s_mul_i32 s20, s20, s17
	s_sub_i32 s12, s12, s20
	s_sub_i32 s20, s12, s17
	s_cmp_ge_u32 s12, s17
	s_cselect_b32 s12, s20, s12
	s_sub_i32 s20, s12, s17
	s_cmp_ge_u32 s12, s17
	s_cselect_b32 s12, s20, s12
	s_xor_b32 s12, s12, s13
	s_sub_i32 s12, s12, s13
	s_add_i32 s16, s16, s12
	s_and_saveexec_b64 s[12:13], s[6:7]
	v_lshl_add_u32 v160, s16, 8, v4
	v_ashrrev_i32_e32 v161, 31, v160
	v_lshlrev_b64 v[160:161], 6, v[160:161]
	v_lshl_add_u64 v[24:25], s[8:9], 0, v[160:161]
	global_load_dwordx4 v[160:163], v[24:25], off
	global_load_dwordx4 v[164:167], v[24:25], off offset:16
	global_load_dwordx4 v[168:171], v[24:25], off offset:32
	global_load_dwordx4 v[172:175], v[24:25], off offset:48
	s_or_b64 exec, exec, s[12:13]
	s_add_u32 s10, s10, s52
	s_addc_u32 s11, s11, s53
	s_ashr_i32 s12, s10, 31
	s_lshr_b32 s12, s12, 29
	s_add_i32 s12, s10, s12
	s_ashr_i32 s13, s12, 3
	s_and_b32 s12, s12, -8
	s_sub_i32 s12, s10, s12
	s_cmp_lt_i32 s12, 0
	s_cselect_b32 s16, s14, 0x160
	s_mul_i32 s12, s12, s16
	s_add_i32 s12, s12, s13
	s_mul_hi_i32 s13, s12, 0x2e8ba2e9
	s_lshr_b32 s16, s13, 31
	s_ashr_i32 s13, s13, 4
	s_add_i32 s13, s13, s16
	s_lshl_b32 s16, s13, 2
	s_sub_i32 s17, 0x80, s16
	s_min_i32 s17, s17, 4
	s_abs_i32 s17, s17
	v_cvt_f32_u32_e32 v7, s17
	s_sub_i32 s20, 0, s17
	s_mul_i32 s13, s13, 88
	s_sub_i32 s12, s12, s13
	v_rcp_iflag_f32_e32 v7, v7
	s_ashr_i32 s13, s12, 31
	s_abs_i32 s12, s12
	v_mul_f32_e32 v7, 0x4f7ffffe, v7
	v_cvt_u32_f32_e32 v7, v7
	s_nop 0
	v_readfirstlane_b32 s21, v7
	s_mul_i32 s20, s20, s21
	s_mul_hi_u32 s20, s21, s20
	s_add_i32 s21, s21, s20
	s_mul_hi_u32 s20, s12, s21
	s_mul_i32 s20, s20, s17
	s_sub_i32 s12, s12, s20
	s_sub_i32 s20, s12, s17
	s_cmp_ge_u32 s12, s17
	s_cselect_b32 s12, s20, s12
	s_sub_i32 s20, s12, s17
	s_cmp_ge_u32 s12, s17
	s_cselect_b32 s12, s20, s12
	s_xor_b32 s12, s12, s13
	s_sub_i32 s12, s12, s13
	s_add_i32 s16, s16, s12
	s_and_saveexec_b64 s[12:13], s[6:7]
	v_lshl_add_u32 v176, s16, 8, v4
	v_ashrrev_i32_e32 v177, 31, v176
	v_lshlrev_b64 v[176:177], 6, v[176:177]
	v_lshl_add_u64 v[24:25], s[8:9], 0, v[176:177]
	global_load_dwordx4 v[176:179], v[24:25], off
	global_load_dwordx4 v[180:183], v[24:25], off offset:16
	global_load_dwordx4 v[184:187], v[24:25], off offset:32
	global_load_dwordx4 v[188:191], v[24:25], off offset:48
	s_or_b64 exec, exec, s[12:13]
	s_add_u32 s10, s10, s52
	s_addc_u32 s11, s11, s53
	s_ashr_i32 s12, s10, 31
	s_lshr_b32 s12, s12, 29
	s_add_i32 s12, s10, s12
	s_ashr_i32 s13, s12, 3
	s_and_b32 s12, s12, -8
	s_sub_i32 s12, s10, s12
	s_cmp_lt_i32 s12, 0
	s_cselect_b32 s16, s14, 0x160
	s_mul_i32 s12, s12, s16
	s_add_i32 s12, s12, s13
	s_mul_hi_i32 s13, s12, 0x2e8ba2e9
	s_lshr_b32 s16, s13, 31
	s_ashr_i32 s13, s13, 4
	s_add_i32 s13, s13, s16
	s_lshl_b32 s16, s13, 2
	s_sub_i32 s17, 0x80, s16
	s_min_i32 s17, s17, 4
	s_abs_i32 s17, s17
	v_cvt_f32_u32_e32 v7, s17
	s_sub_i32 s20, 0, s17
	s_mul_i32 s13, s13, 88
	s_sub_i32 s12, s12, s13
	v_rcp_iflag_f32_e32 v7, v7
	s_ashr_i32 s13, s12, 31
	s_abs_i32 s12, s12
	v_mul_f32_e32 v7, 0x4f7ffffe, v7
	v_cvt_u32_f32_e32 v7, v7
	s_nop 0
	v_readfirstlane_b32 s21, v7
	s_mul_i32 s20, s20, s21
	s_mul_hi_u32 s20, s21, s20
	s_add_i32 s21, s21, s20
	s_mul_hi_u32 s20, s12, s21
	s_mul_i32 s20, s20, s17
	s_sub_i32 s12, s12, s20
	s_sub_i32 s20, s12, s17
	s_cmp_ge_u32 s12, s17
	s_cselect_b32 s12, s20, s12
	s_sub_i32 s20, s12, s17
	s_cmp_ge_u32 s12, s17
	s_cselect_b32 s12, s20, s12
	s_xor_b32 s12, s12, s13
	s_sub_i32 s12, s12, s13
	s_add_i32 s16, s16, s12
	s_and_saveexec_b64 s[12:13], s[6:7]
	v_lshl_add_u32 v192, s16, 8, v4
	v_ashrrev_i32_e32 v193, 31, v192
	v_lshlrev_b64 v[192:193], 6, v[192:193]
	v_lshl_add_u64 v[24:25], s[8:9], 0, v[192:193]
	global_load_dwordx4 v[192:195], v[24:25], off
	global_load_dwordx4 v[196:199], v[24:25], off offset:16
	global_load_dwordx4 v[200:203], v[24:25], off offset:32
	global_load_dwordx4 v[204:207], v[24:25], off offset:48
	s_or_b64 exec, exec, s[12:13]
	s_and_saveexec_b64 s[12:13], s[6:7]
	s_waitcnt vmcnt(0)
; __device__ __forceinline__ float row_rstd(const float* ssq, int row) {
;     const f32x4* p = (const f32x4*)(ssq + (size_t)row * 16);
;     const f32x4 a = p[0], b = p[1], c = p[2], d = p[3];
;     const float s = ((a[0] + a[1]) + (a[2] + a[3])) + ((b[0] + b[1]) + (b[2] + b[3])) + ((c[0] + c[1]) + (c[2] + c[3])) + ((d[0] + d[1]) + (d[2] + d[3]));
;     return rsqrtf(s * (1.0f / 1024.0f) + EPS);
; __global__ void __launch_bounds__(512, 2) hybrid_fwd(Args args) {
;     ...
;         { pg8::Unit pu; for (int i = 0; S.next(i, pu); ++i) if (tid < 256) rst[i * 256 + tid] = row_rstd(SSQ + SSQ_STRIDE, pu.pm * 256 + tid);
	v_mov_b32_e32 v24, v33
	v_mov_b32_e32 v25, v34
	v_mov_b32_e32 v33, v35
	v_mov_b32_e32 v34, v37
	v_mov_b32_e32 v35, v38
	v_mov_b32_e32 v37, v39
	v_pk_add_f32 v[32:33], v[24:25], v[32:33]
	v_pk_add_f32 v[34:35], v[34:35], v[36:37]
	v_pk_add_f32 v[32:33], v[32:33], v[32:33] op_sel:[0,1] op_sel_hi:[1,0]
	v_pk_add_f32 v[34:35], v[34:35], v[34:35] op_sel:[0,1] op_sel_hi:[1,0]
	v_add_f32_e32 v38, v40, v41
	v_add_f32_e32 v40, v42, v43
	v_mov_b32_e32 v39, v46
	v_mov_b32_e32 v41, v47
	v_mov_b32_e32 v33, v44
	v_mov_b32_e32 v35, v45
	v_pk_add_f32 v[36:37], v[38:39], v[40:41]
	v_pk_add_f32 v[32:33], v[32:33], v[34:35]
	s_nop 0
	v_pk_add_f32 v[32:33], v[32:33], v[36:37]
	s_nop 0
	v_add_f32_e32 v7, v32, v33
	v_fmamk_f32 v7, v7, 0x3a800000, v6
	v_mul_f32_e32 v32, 0x4b800000, v7
	v_cmp_gt_f32_e32 vcc, s15, v7
	s_nop 1
	v_cndmask_b32_e32 v7, v7, v32, vcc
	v_rsq_f32_e32 v7, v7
	s_nop 0
	v_mul_f32_e32 v32, 0x45800000, v7
	v_cndmask_b32_e32 v7, v7, v32, vcc
	ds_write_b32 v5, v7
	v_mov_b32_e32 v24, v49
	v_mov_b32_e32 v25, v50
	v_mov_b32_e32 v49, v51
	v_mov_b32_e32 v50, v53
	v_mov_b32_e32 v51, v54
	v_mov_b32_e32 v53, v55
	v_pk_add_f32 v[48:49], v[24:25], v[48:49]
	v_pk_add_f32 v[50:51], v[50:51], v[52:53]
	v_pk_add_f32 v[48:49], v[48:49], v[48:49] op_sel:[0,1] op_sel_hi:[1,0]
	v_pk_add_f32 v[50:51], v[50:51], v[50:51] op_sel:[0,1] op_sel_hi:[1,0]
	v_add_f32_e32 v54, v56, v57
	v_add_f32_e32 v56, v58, v59
	v_mov_b32_e32 v55, v62
	v_mov_b32_e32 v57, v63
	v_mov_b32_e32 v49, v60
	v_mov_b32_e32 v51, v61
	v_pk_add_f32 v[52:53], v[54:55], v[56:57]
	v_pk_add_f32 v[48:49], v[48:49], v[50:51]
	s_nop 0
	v_pk_add_f32 v[48:49], v[48:49], v[52:53]
	s_nop 0
	v_add_f32_e32 v7, v48, v49
	v_fmamk_f32 v7, v7, 0x3a800000, v6
	v_mul_f32_e32 v48, 0x4b800000, v7
	v_cmp_gt_f32_e32 vcc, s15, v7
	s_nop 1
	v_cndmask_b32_e32 v7, v7, v48, vcc
	v_rsq_f32_e32 v7, v7
	s_nop 0
	v_mul_f32_e32 v48, 0x45800000, v7
	v_cndmask_b32_e32 v7, v7, v48, vcc
	ds_write_b32 v5, v7 offset:1024
	v_mov_b32_e32 v24, v65
	v_mov_b32_e32 v25, v66
	v_mov_b32_e32 v65, v67
	v_mov_b32_e32 v66, v69
	v_mov_b32_e32 v67, v70
	v_mov_b32_e32 v69, v71
	v_pk_add_f32 v[64:65], v[24:25], v[64:65]
	v_pk_add_f32 v[66:67], v[66:67], v[68:69]
	v_pk_add_f32 v[64:65], v[64:65], v[64:65] op_sel:[0,1] op_sel_hi:[1,0]
	v_pk_add_f32 v[66:67], v[66:67], v[66:67] op_sel:[0,1] op_sel_hi:[1,0]
	v_add_f32_e32 v70, v72, v73
	v_add_f32_e32 v72, v74, v75
	v_mov_b32_e32 v71, v78
	v_mov_b32_e32 v73, v79
	v_mov_b32_e32 v65, v76
	v_mov_b32_e32 v67, v77
	v_pk_add_f32 v[68:69], v[70:71], v[72:73]
	v_pk_add_f32 v[64:65], v[64:65], v[66:67]
	s_nop 0
	v_pk_add_f32 v[64:65], v[64:65], v[68:69]
	s_nop 0
	v_add_f32_e32 v7, v64, v65
	v_fmamk_f32 v7, v7, 0x3a800000, v6
	v_mul_f32_e32 v64, 0x4b800000, v7
	v_cmp_gt_f32_e32 vcc, s15, v7
	s_nop 1
	v_cndmask_b32_e32 v7, v7, v64, vcc
	v_rsq_f32_e32 v7, v7
	s_nop 0
	v_mul_f32_e32 v64, 0x45800000, v7
	v_cndmask_b32_e32 v7, v7, v64, vcc
	ds_write_b32 v5, v7 offset:2048
	v_mov_b32_e32 v24, v81
	v_mov_b32_e32 v25, v82
	v_mov_b32_e32 v81, v83
	v_mov_b32_e32 v82, v85
	v_mov_b32_e32 v83, v86
	v_mov_b32_e32 v85, v87
	v_pk_add_f32 v[80:81], v[24:25], v[80:81]
	v_pk_add_f32 v[82:83], v[82:83], v[84:85]
	v_pk_add_f32 v[80:81], v[80:81], v[80:81] op_sel:[0,1] op_sel_hi:[1,0]
	v_pk_add_f32 v[82:83], v[82:83], v[82:83] op_sel:[0,1] op_sel_hi:[1,0]
	v_add_f32_e32 v86, v88, v89
	v_add_f32_e32 v88, v90, v91
	v_mov_b32_e32 v87, v94
	v_mov_b32_e32 v89, v95
	v_mov_b32_e32 v81, v92
	v_mov_b32_e32 v83, v93
	v_pk_add_f32 v[84:85], v[86:87], v[88:89]
	v_pk_add_f32 v[80:81], v[80:81], v[82:83]
	s_nop 0
	v_pk_add_f32 v[80:81], v[80:81], v[84:85]
	s_nop 0
	v_add_f32_e32 v7, v80, v81
	v_fmamk_f32 v7, v7, 0x3a800000, v6
	v_mul_f32_e32 v80, 0x4b800000, v7
	v_cmp_gt_f32_e32 vcc, s15, v7
	s_nop 1
	v_cndmask_b32_e32 v7, v7, v80, vcc
	v_rsq_f32_e32 v7, v7
	s_nop 0
	v_mul_f32_e32 v80, 0x45800000, v7
	v_cndmask_b32_e32 v7, v7, v80, vcc
	ds_write_b32 v5, v7 offset:3072
	v_mov_b32_e32 v24, v97
	v_mov_b32_e32 v25, v98
	v_mov_b32_e32 v97, v99
	v_mov_b32_e32 v98, v101
	v_mov_b32_e32 v99, v102
	v_mov_b32_e32 v101, v103
	v_pk_add_f32 v[96:97], v[24:25], v[96:97]
	v_pk_add_f32 v[98:99], v[98:99], v[100:101]
	v_pk_add_f32 v[96:97], v[96:97], v[96:97] op_sel:[0,1] op_sel_hi:[1,0]
	v_pk_add_f32 v[98:99], v[98:99], v[98:99] op_sel:[0,1] op_sel_hi:[1,0]
	v_add_f32_e32 v102, v104, v105
	v_add_f32_e32 v104, v106, v107
	v_mov_b32_e32 v103, v110
	v_mov_b32_e32 v105, v111
	v_mov_b32_e32 v97, v108
	v_mov_b32_e32 v99, v109
	v_pk_add_f32 v[100:101], v[102:103], v[104:105]
	v_pk_add_f32 v[96:97], v[96:97], v[98:99]
	s_nop 0
	v_pk_add_f32 v[96:97], v[96:97], v[100:101]
	s_nop 0
	v_add_f32_e32 v7, v96, v97
	v_fmamk_f32 v7, v7, 0x3a800000, v6
	v_mul_f32_e32 v96, 0x4b800000, v7
	v_cmp_gt_f32_e32 vcc, s15, v7
	s_nop 1
	v_cndmask_b32_e32 v7, v7, v96, vcc
	v_rsq_f32_e32 v7, v7
	s_nop 0
	v_mul_f32_e32 v96, 0x45800000, v7
	v_cndmask_b32_e32 v7, v7, v96, vcc
	ds_write_b32 v5, v7 offset:4096
	v_mov_b32_e32 v24, v113
	v_mov_b32_e32 v25, v114
	v_mov_b32_e32 v113, v115
	v_mov_b32_e32 v114, v117
	v_mov_b32_e32 v115, v118
	v_mov_b32_e32 v117, v119
	v_pk_add_f32 v[112:113], v[24:25], v[112:113]
	v_pk_add_f32 v[114:115], v[114:115], v[116:117]
	v_pk_add_f32 v[112:113], v[112:113], v[112:113] op_sel:[0,1] op_sel_hi:[1,0]
	v_pk_add_f32 v[114:115], v[114:115], v[114:115] op_sel:[0,1] op_sel_hi:[1,0]
	v_add_f32_e32 v118, v120, v121
	v_add_f32_e32 v120, v122, v123
	v_mov_b32_e32 v119, v126
	v_mov_b32_e32 v121, v127
	v_mov_b32_e32 v113, v124
	v_mov_b32_e32 v115, v125
	v_pk_add_f32 v[116:117], v[118:119], v[120:121]
	v_pk_add_f32 v[112:113], v[112:113], v[114:115]
	s_nop 0
; __device__ __forceinline__ float row_rstd(const float* ssq, int row) {
;     const f32x4* p = (const f32x4*)(ssq + (size_t)row * 16);
;     const f32x4 a = p[0], b = p[1], c = p[2], d = p[3];
;     const float s = ((a[0] + a[1]) + (a[2] + a[3])) + ((b[0] + b[1]) + (b[2] + b[3])) + ((c[0] + c[1]) + (c[2] + c[3])) + ((d[0] + d[1]) + (d[2] + d[3]));
;     return rsqrtf(s * (1.0f / 1024.0f) + EPS);
; __global__ void __launch_bounds__(512, 2) hybrid_fwd(Args args) {
;     ...
;         { pg8::Unit pu; for (int i = 0; S.next(i, pu); ++i) if (tid < 256) rst[i * 256 + tid] = row_rstd(SSQ + SSQ_STRIDE, pu.pm * 256 + tid);
	v_pk_add_f32 v[112:113], v[112:113], v[116:117]
	s_nop 0
	v_add_f32_e32 v7, v112, v113
	v_fmamk_f32 v7, v7, 0x3a800000, v6
	v_mul_f32_e32 v112, 0x4b800000, v7
	v_cmp_gt_f32_e32 vcc, s15, v7
	s_nop 1
	v_cndmask_b32_e32 v7, v7, v112, vcc
	v_rsq_f32_e32 v7, v7
	s_nop 0
	v_mul_f32_e32 v112, 0x45800000, v7
	v_cndmask_b32_e32 v7, v7, v112, vcc
	ds_write_b32 v5, v7 offset:5120
	v_mov_b32_e32 v24, v129
	v_mov_b32_e32 v25, v130
	v_mov_b32_e32 v129, v131
	v_mov_b32_e32 v130, v133
	v_mov_b32_e32 v131, v134
	v_mov_b32_e32 v133, v135
	v_pk_add_f32 v[128:129], v[24:25], v[128:129]
	v_pk_add_f32 v[130:131], v[130:131], v[132:133]
	v_pk_add_f32 v[128:129], v[128:129], v[128:129] op_sel:[0,1] op_sel_hi:[1,0]
	v_pk_add_f32 v[130:131], v[130:131], v[130:131] op_sel:[0,1] op_sel_hi:[1,0]
	v_add_f32_e32 v134, v136, v137
	v_add_f32_e32 v136, v138, v139
	v_mov_b32_e32 v135, v142
	v_mov_b32_e32 v137, v143
	v_mov_b32_e32 v129, v140
	v_mov_b32_e32 v131, v141
	v_pk_add_f32 v[132:133], v[134:135], v[136:137]
	v_pk_add_f32 v[128:129], v[128:129], v[130:131]
	s_nop 0
	v_pk_add_f32 v[128:129], v[128:129], v[132:133]
	s_nop 0
	v_add_f32_e32 v7, v128, v129
	v_fmamk_f32 v7, v7, 0x3a800000, v6
	v_mul_f32_e32 v128, 0x4b800000, v7
	v_cmp_gt_f32_e32 vcc, s15, v7
	s_nop 1
	v_cndmask_b32_e32 v7, v7, v128, vcc
	v_rsq_f32_e32 v7, v7
	s_nop 0
	v_mul_f32_e32 v128, 0x45800000, v7
	v_cndmask_b32_e32 v7, v7, v128, vcc
	ds_write_b32 v5, v7 offset:6144
	v_mov_b32_e32 v24, v145
	v_mov_b32_e32 v25, v146
	v_mov_b32_e32 v145, v147
	v_mov_b32_e32 v146, v149
	v_mov_b32_e32 v147, v150
	v_mov_b32_e32 v149, v151
	v_pk_add_f32 v[144:145], v[24:25], v[144:145]
	v_pk_add_f32 v[146:147], v[146:147], v[148:149]
	v_pk_add_f32 v[144:145], v[144:145], v[144:145] op_sel:[0,1] op_sel_hi:[1,0]
	v_pk_add_f32 v[146:147], v[146:147], v[146:147] op_sel:[0,1] op_sel_hi:[1,0]
	v_add_f32_e32 v150, v152, v153
	v_add_f32_e32 v152, v154, v155
	v_mov_b32_e32 v151, v158
	v_mov_b32_e32 v153, v159
	v_mov_b32_e32 v145, v156
	v_mov_b32_e32 v147, v157
	v_pk_add_f32 v[148:149], v[150:151], v[152:153]
	v_pk_add_f32 v[144:145], v[144:145], v[146:147]
	s_nop 0
	v_pk_add_f32 v[144:145], v[144:145], v[148:149]
	s_nop 0
	v_add_f32_e32 v7, v144, v145
	v_fmamk_f32 v7, v7, 0x3a800000, v6
	v_mul_f32_e32 v144, 0x4b800000, v7
	v_cmp_gt_f32_e32 vcc, s15, v7
	s_nop 1
	v_cndmask_b32_e32 v7, v7, v144, vcc
	v_rsq_f32_e32 v7, v7
	s_nop 0
	v_mul_f32_e32 v144, 0x45800000, v7
	v_cndmask_b32_e32 v7, v7, v144, vcc
	ds_write_b32 v5, v7 offset:7168
	v_mov_b32_e32 v24, v161
	v_mov_b32_e32 v25, v162
	v_mov_b32_e32 v161, v163
	v_mov_b32_e32 v162, v165
	v_mov_b32_e32 v163, v166
	v_mov_b32_e32 v165, v167
	v_pk_add_f32 v[160:161], v[24:25], v[160:161]
	v_pk_add_f32 v[162:163], v[162:163], v[164:165]
	v_pk_add_f32 v[160:161], v[160:161], v[160:161] op_sel:[0,1] op_sel_hi:[1,0]
	v_pk_add_f32 v[162:163], v[162:163], v[162:163] op_sel:[0,1] op_sel_hi:[1,0]
	v_add_f32_e32 v166, v168, v169
	v_add_f32_e32 v168, v170, v171
	v_mov_b32_e32 v167, v174
	v_mov_b32_e32 v169, v175
	v_mov_b32_e32 v161, v172
	v_mov_b32_e32 v163, v173
	v_pk_add_f32 v[164:165], v[166:167], v[168:169]
	v_pk_add_f32 v[160:161], v[160:161], v[162:163]
	s_nop 0
	v_pk_add_f32 v[160:161], v[160:161], v[164:165]
	s_nop 0
	v_add_f32_e32 v7, v160, v161
	v_fmamk_f32 v7, v7, 0x3a800000, v6
	v_mul_f32_e32 v160, 0x4b800000, v7
	v_cmp_gt_f32_e32 vcc, s15, v7
	s_nop 1
	v_cndmask_b32_e32 v7, v7, v160, vcc
	v_rsq_f32_e32 v7, v7
	s_nop 0
	v_mul_f32_e32 v160, 0x45800000, v7
	v_cndmask_b32_e32 v7, v7, v160, vcc
	ds_write_b32 v5, v7 offset:8192
	v_mov_b32_e32 v24, v177
	v_mov_b32_e32 v25, v178
	v_mov_b32_e32 v177, v179
	v_mov_b32_e32 v178, v181
	v_mov_b32_e32 v179, v182
	v_mov_b32_e32 v181, v183
	v_pk_add_f32 v[176:177], v[24:25], v[176:177]
	v_pk_add_f32 v[178:179], v[178:179], v[180:181]
	v_pk_add_f32 v[176:177], v[176:177], v[176:177] op_sel:[0,1] op_sel_hi:[1,0]
	v_pk_add_f32 v[178:179], v[178:179], v[178:179] op_sel:[0,1] op_sel_hi:[1,0]
	v_add_f32_e32 v182, v184, v185
	v_add_f32_e32 v184, v186, v187
	v_mov_b32_e32 v183, v190
	v_mov_b32_e32 v185, v191
	v_mov_b32_e32 v177, v188
	v_mov_b32_e32 v179, v189
	v_pk_add_f32 v[180:181], v[182:183], v[184:185]
	v_pk_add_f32 v[176:177], v[176:177], v[178:179]
	s_nop 0
	v_pk_add_f32 v[176:177], v[176:177], v[180:181]
	s_nop 0
	v_add_f32_e32 v7, v176, v177
	v_fmamk_f32 v7, v7, 0x3a800000, v6
	v_mul_f32_e32 v176, 0x4b800000, v7
	v_cmp_gt_f32_e32 vcc, s15, v7
	s_nop 1
	v_cndmask_b32_e32 v7, v7, v176, vcc
	v_rsq_f32_e32 v7, v7
	s_nop 0
	v_mul_f32_e32 v176, 0x45800000, v7
	v_cndmask_b32_e32 v7, v7, v176, vcc
	ds_write_b32 v5, v7 offset:9216
	v_mov_b32_e32 v24, v193
	v_mov_b32_e32 v25, v194
	v_mov_b32_e32 v193, v195
	v_mov_b32_e32 v194, v197
	v_mov_b32_e32 v195, v198
	v_mov_b32_e32 v197, v199
	v_pk_add_f32 v[192:193], v[24:25], v[192:193]
	v_pk_add_f32 v[194:195], v[194:195], v[196:197]
	v_pk_add_f32 v[192:193], v[192:193], v[192:193] op_sel:[0,1] op_sel_hi:[1,0]
	v_pk_add_f32 v[194:195], v[194:195], v[194:195] op_sel:[0,1] op_sel_hi:[1,0]
	v_add_f32_e32 v198, v200, v201
	v_add_f32_e32 v200, v202, v203
	v_mov_b32_e32 v199, v206
	v_mov_b32_e32 v201, v207
	v_mov_b32_e32 v193, v204
	v_mov_b32_e32 v195, v205
	v_pk_add_f32 v[196:197], v[198:199], v[200:201]
	v_pk_add_f32 v[192:193], v[192:193], v[194:195]
	s_nop 0
	v_pk_add_f32 v[192:193], v[192:193], v[196:197]
	s_nop 0
	v_add_f32_e32 v7, v192, v193
	v_fmamk_f32 v7, v7, 0x3a800000, v6
	v_mul_f32_e32 v192, 0x4b800000, v7
	v_cmp_gt_f32_e32 vcc, s15, v7
	s_nop 1
	v_cndmask_b32_e32 v7, v7, v192, vcc
	v_rsq_f32_e32 v7, v7
	s_nop 0
	v_mul_f32_e32 v192, 0x45800000, v7
	v_cndmask_b32_e32 v7, v7, v192, vcc
	ds_write_b32 v5, v7 offset:10240
	s_or_b64 exec, exec, s[12:13]
	s_branch .LBB0_585

;     __device__ __forceinline__ bool next(int i, Unit& u) const {
;         const long L = (long)i * G + c; if (L >= nwg) return false;
;         int wgid = (int)L; { const int q = nwg / NXCD, r = nwg % NXCD, xcd = wgid % NXCD, off = wgid / NXCD; wgid = (xcd < r ? xcd * (q + 1) : r * (q + 1) + (xcd - r) * q) + off; }
;         const int nig = WGM * nN, gid = wgid / nig, fm = gid * WGM, gsz = (nM - fm) < WGM ? (nM - fm) : WGM;
;         u.pm = fm + ((wgid % nig) % gsz); u.pn = (wgid % nig) / gsz; u.idx = i; return true;
;     }
; __global__ void __launch_bounds__(512, 2) hybrid_fwd(Args args) {
;     ...
;         { pg8::Unit pu; for (int i = 0; S.next(i, pu); ++i) if (tid < 256) rst[i * 256 + tid] = row_rstd(SSQ + SSQ_STRIDE, pu.pm * 256 + tid);
.LBB0_582:
	s_ashr_i32 s12, s10, 31
	s_lshr_b32 s12, s12, 29
	s_add_i32 s12, s10, s12
	s_ashr_i32 s13, s12, 3
	s_and_b32 s12, s12, -8
	s_sub_i32 s12, s10, s12
	s_cmp_lt_i32 s12, 0
	s_cselect_b32 s16, s14, 0x160
	s_mul_i32 s12, s12, s16
	s_add_i32 s12, s12, s13
	s_mul_hi_i32 s13, s12, 0x2e8ba2e9
	s_lshr_b32 s16, s13, 31
	s_ashr_i32 s13, s13, 4
	s_add_i32 s13, s13, s16
	s_lshl_b32 s16, s13, 2
	s_sub_i32 s17, 0x80, s16
	s_min_i32 s17, s17, 4
	s_abs_i32 s17, s17
	v_cvt_f32_u32_e32 v7, s17
	s_sub_i32 s20, 0, s17
	s_mul_i32 s13, s13, 88
	s_sub_i32 s12, s12, s13
	v_rcp_iflag_f32_e32 v7, v7
	s_ashr_i32 s13, s12, 31
	s_abs_i32 s12, s12
	v_mul_f32_e32 v7, 0x4f7ffffe, v7
	v_cvt_u32_f32_e32 v7, v7
	s_nop 0
	v_readfirstlane_b32 s21, v7
	s_mul_i32 s20, s20, s21
	s_mul_hi_u32 s20, s21, s20
	s_add_i32 s21, s21, s20
	s_mul_hi_u32 s20, s12, s21
	s_mul_i32 s20, s20, s17
	s_sub_i32 s12, s12, s20
	s_sub_i32 s20, s12, s17
	s_cmp_ge_u32 s12, s17
	s_cselect_b32 s12, s20, s12
	s_sub_i32 s20, s12, s17
	s_cmp_ge_u32 s12, s17
	s_cselect_b32 s12, s20, s12
	s_xor_b32 s12, s12, s13
	s_sub_i32 s12, s12, s13
	s_add_i32 s16, s16, s12
	v_cmp_lt_i64_e32 vcc, s[10:11], v[0:1]
	s_mov_b64 s[12:13], -1
	s_cbranch_vccz .LBB0_579

;     __device__ __forceinline__ bool next(int i, Unit& u) const {
;         const long L = (long)i * G + c; if (L >= nwg) return false;
;         int wgid = (int)L; { const int q = nwg / NXCD, r = nwg % NXCD, xcd = wgid % NXCD, off = wgid / NXCD; wgid = (xcd < r ? xcd * (q + 1) : r * (q + 1) + (xcd - r) * q) + off; }
;         const int nig = WGM * nN, gid = wgid / nig, fm = gid * WGM, gsz = (nM - fm) < WGM ? (nM - fm) : WGM;
;         u.pm = fm + ((wgid % nig) % gsz); u.pn = (wgid % nig) / gsz; u.idx = i; return true;
;     }
; template <class Epi, bool HALO>
; __device__ __forceinline__ void gemm_phase(LAS unsigned char* lds, const Gemm g, const StaticOrder& S, const Epi& E) {
;     ...
;     if (!S.next(0, cur)) return;
.LBB0_585:
	v_mov_b32_e32 v4, v220
	s_cmpk_lt_i32 s2, 0xb00
	s_waitcnt vmcnt(0) lgkmcnt(0)
	s_barrier
	s_cselect_b64 s[6:7], -1, 0
	s_cmpk_gt_i32 s2, 0xaff
	v_readfirstlane_b32 s12, v4
	s_cbranch_scc1 .LBB0_587
	s_ashr_i32 s8, s2, 31
	s_lshr_b32 s8, s8, 29
	s_add_i32 s8, s2, s8
	s_ashr_i32 s9, s8, 3
	s_and_b32 s8, s8, -8
	s_sub_i32 s8, s2, s8
	s_cmp_lt_i32 s8, 0
	s_movk_i32 s10, 0x161
	s_cselect_b32 s10, s10, 0x160
	s_mul_i32 s8, s8, s10
	s_add_i32 s8, s8, s9
	s_mul_hi_i32 s9, s8, 0x2e8ba2e9
	s_lshr_b32 s10, s9, 31
	s_ashr_i32 s9, s9, 4
	s_add_i32 s9, s9, s10
	s_lshl_b32 s10, s9, 2
	s_mul_i32 s9, s9, 88
	s_sub_i32 s8, s8, s9
	s_and_b32 s9, s8, 3
	s_add_i32 s14, s10, s9
	s_lshr_b32 s40, s8, 2

;     __device__ __forceinline__ bool next(int i, Unit& u) const {
;         const long L = (long)i * G + c; if (L >= nwg) return false;
;         int wgid = (int)L; { const int q = nwg / NXCD, r = nwg % NXCD, xcd = wgid % NXCD, off = wgid / NXCD; wgid = (xcd < r ? xcd * (q + 1) : r * (q + 1) + (xcd - r) * q) + off; }
;         const int nig = WGM * nN, gid = wgid / nig, fm = gid * WGM, gsz = (nM - fm) < WGM ? (nM - fm) : WGM;
;         u.pm = fm + ((wgid % nig) % gsz); u.pn = (wgid % nig) / gsz; u.idx = i; return true;
;     }
; template <class Epi, bool HALO>
; __device__ __forceinline__ void gemm_phase(LAS unsigned char* lds, const Gemm g, const StaticOrder& S, const Epi& E) {
;     ...
;         const bool has_next = S.next(ui + 1, nxt);
.LBB0_593:
	s_add_i32 s91, s91, 1
	s_mul_i32 s6, s91, s53
	s_mul_hi_u32 s7, s91, s52
	s_add_i32 s7, s7, s6
	s_mul_i32 s6, s91, s52
	s_add_u32 s12, s6, s2
	s_addc_u32 s13, s7, s3
	v_cmp_gt_i64_e32 vcc, s[12:13], v[192:193]
	v_cmp_lt_i64_e64 s[6:7], s[12:13], v[190:191]
	s_cbranch_vccnz .LBB0_595
	s_ashr_i32 s13, s12, 31
	s_lshr_b32 s13, s13, 29
	s_add_i32 s13, s12, s13
	s_ashr_i32 s16, s13, 3
	s_and_b32 s13, s13, -8
	s_sub_i32 s12, s12, s13
	s_cmp_lt_i32 s12, 0
	s_cselect_b32 s13, s71, 0x160
	s_mul_i32 s12, s12, s13
	s_add_i32 s12, s12, s16
	s_mul_hi_i32 s13, s12, 0x2e8ba2e9
	s_lshr_b32 s16, s13, 31
	s_ashr_i32 s13, s13, 4
	s_add_i32 s13, s13, s16
	s_lshl_b32 s16, s13, 2
	s_sub_i32 s17, 0x80, s16
	s_min_i32 s17, s17, 4
	s_abs_i32 s30, s17
	v_cvt_f32_u32_e32 v0, s30
	s_sub_i32 s34, 0, s30
	s_mul_i32 s13, s13, 88
	s_sub_i32 s12, s12, s13
	v_rcp_iflag_f32_e32 v0, v0
	s_abs_i32 s13, s12
	s_xor_b32 s31, s12, s17
	s_ashr_i32 s31, s31, 31
	v_mul_f32_e32 v0, 0x4f7ffffe, v0
	v_cvt_u32_f32_e32 v0, v0
	s_mov_b32 s92, s91
	v_readfirstlane_b32 s35, v0
	s_mul_i32 s34, s34, s35
	s_mul_hi_u32 s34, s35, s34
	s_add_i32 s35, s35, s34
	s_mul_hi_u32 s34, s13, s35
	s_mul_i32 s35, s34, s30
	s_sub_i32 s13, s13, s35
	s_add_i32 s36, s34, 1
	s_sub_i32 s35, s13, s30
	s_cmp_ge_u32 s13, s30
	s_cselect_b32 s34, s36, s34
	s_cselect_b32 s13, s35, s13
	s_add_i32 s35, s34, 1
	s_cmp_ge_u32 s13, s30
	s_cselect_b32 s13, s35, s34
	s_xor_b32 s13, s13, s31
	s_sub_i32 s30, s13, s31
	s_mul_i32 s13, s30, s17
	s_sub_i32 s12, s12, s13
	s_add_i32 s34, s16, s12

;     __device__ __forceinline__ bool next(int i, Unit& u) const {
;         const long L = (long)i * G + c; if (L >= nwg) return false;
;         int wgid = (int)L; { const int q = nwg / NXCD, r = nwg % NXCD, xcd = wgid % NXCD, off = wgid / NXCD; wgid = (xcd < r ? xcd * (q + 1) : r * (q + 1) + (xcd - r) * q) + off; }
;         const int nig = WGM * nN, gid = wgid / nig, fm = gid * WGM, gsz = (nM - fm) < WGM ? (nM - fm) : WGM;
;         u.pm = fm + ((wgid % nig) % gsz); u.pn = (wgid % nig) / gsz; u.idx = i; return true;
;     }
; __global__ void __launch_bounds__(512, 2) hybrid_fwd(Args args) {
;     ...
;         { pg8::Unit pu; for (int i = 0; S.next(i, pu); ++i) if (tid < 256) rst[i * 256 + tid] = row_rstd(SSQ + 3 * SSQ_STRIDE, pu.pm * 256 + tid);
.LBB0_1258:
	s_cmp_lt_i32 s82, 13
	s_cselect_b64 s[8:9], -1, 0
	s_and_b64 s[18:19], s[8:9], s[6:7]
	s_andn2_b64 vcc, exec, s[18:19]
	s_cbranch_vccnz .LBB0_1318
	v_mov_b32_e32 v4, v220
	s_load_dword s46, s[0:1], 0xb0
	s_waitcnt lgkmcnt(0)
	s_ashr_i32 s3, s2, 31
	s_movk_i32 s6, 0x100
	v_lshl_add_u32 v0, v4, 2, 0
	v_cmp_gt_i32_e64 s[6:7], s6, v4
	s_ashr_i32 s47, s46, 31
	s_add_u32 s8, s80, 0x3a00000
	s_addc_u32 s9, s81, 0
	v_add_u32_e32 v5, 0x22000, v0
	v_mov_b64_e32 v[0:1], 0xb00
	v_mov_b64_e32 v[2:3], 0xaff
	s_movk_i32 s14, 0x161
	v_mov_b32_e32 v6, 0x358637bd
	s_mov_b32 s15, 0x800000
	s_mov_b64 s[10:11], s[2:3]
	s_cmp_lg_u32 s46, 0x100
	s_cbranch_scc1 .Lrs3_slow
	s_ashr_i32 s12, s10, 31
	s_lshr_b32 s12, s12, 29
	s_add_i32 s12, s10, s12
	s_ashr_i32 s13, s12, 3
	s_and_b32 s12, s12, -8
	s_sub_i32 s12, s10, s12
	s_cmp_lt_i32 s12, 0
	s_cselect_b32 s16, s14, 0x160
	s_mul_i32 s12, s12, s16
	s_add_i32 s12, s12, s13
	s_mul_hi_i32 s13, s12, 0x2e8ba2e9
	s_lshr_b32 s16, s13, 31
	s_ashr_i32 s13, s13, 4
	s_add_i32 s13, s13, s16
	s_lshl_b32 s16, s13, 2
	s_sub_i32 s17, 0x80, s16
	s_min_i32 s17, s17, 4
	s_abs_i32 s17, s17
	v_cvt_f32_u32_e32 v7, s17
	s_sub_i32 s20, 0, s17
	s_mul_i32 s13, s13, 88
	s_sub_i32 s12, s12, s13
	v_rcp_iflag_f32_e32 v7, v7
	s_ashr_i32 s13, s12, 31
	s_abs_i32 s12, s12
	v_mul_f32_e32 v7, 0x4f7ffffe, v7
	v_cvt_u32_f32_e32 v7, v7
	s_nop 0
	v_readfirstlane_b32 s21, v7
	s_mul_i32 s20, s20, s21
	s_mul_hi_u32 s20, s21, s20
	s_add_i32 s21, s21, s20
	s_mul_hi_u32 s20, s12, s21
	s_mul_i32 s20, s20, s17
	s_sub_i32 s12, s12, s20
	s_sub_i32 s20, s12, s17
	s_cmp_ge_u32 s12, s17
	s_cselect_b32 s12, s20, s12
	s_sub_i32 s20, s12, s17
	s_cmp_ge_u32 s12, s17
	s_cselect_b32 s12, s20, s12
	s_xor_b32 s12, s12, s13
	s_sub_i32 s12, s12, s13
	s_add_i32 s16, s16, s12
	s_and_saveexec_b64 s[12:13], s[6:7]
	v_lshl_add_u32 v32, s16, 8, v4
	v_ashrrev_i32_e32 v33, 31, v32
	v_lshlrev_b64 v[32:33], 6, v[32:33]
	v_lshl_add_u64 v[24:25], s[8:9], 0, v[32:33]
	global_load_dwordx4 v[32:35], v[24:25], off
	global_load_dwordx4 v[36:39], v[24:25], off offset:16
	global_load_dwordx4 v[40:43], v[24:25], off offset:32
	global_load_dwordx4 v[44:47], v[24:25], off offset:48
	s_or_b64 exec, exec, s[12:13]
	s_add_u32 s10, s10, s46
	s_addc_u32 s11, s11, s47
	s_ashr_i32 s12, s10, 31
	s_lshr_b32 s12, s12, 29
	s_add_i32 s12, s10, s12
	s_ashr_i32 s13, s12, 3
	s_and_b32 s12, s12, -8
	s_sub_i32 s12, s10, s12
	s_cmp_lt_i32 s12, 0
	s_cselect_b32 s16, s14, 0x160
	s_mul_i32 s12, s12, s16
	s_add_i32 s12, s12, s13
	s_mul_hi_i32 s13, s12, 0x2e8ba2e9
	s_lshr_b32 s16, s13, 31
	s_ashr_i32 s13, s13, 4
	s_add_i32 s13, s13, s16
	s_lshl_b32 s16, s13, 2
	s_sub_i32 s17, 0x80, s16
	s_min_i32 s17, s17, 4
	s_abs_i32 s17, s17
	v_cvt_f32_u32_e32 v7, s17
	s_sub_i32 s20, 0, s17
	s_mul_i32 s13, s13, 88
	s_sub_i32 s12, s12, s13
	v_rcp_iflag_f32_e32 v7, v7
	s_ashr_i32 s13, s12, 31
	s_abs_i32 s12, s12
	v_mul_f32_e32 v7, 0x4f7ffffe, v7
	v_cvt_u32_f32_e32 v7, v7
	s_nop 0
	v_readfirstlane_b32 s21, v7
	s_mul_i32 s20, s20, s21
	s_mul_hi_u32 s20, s21, s20
	s_add_i32 s21, s21, s20
	s_mul_hi_u32 s20, s12, s21
	s_mul_i32 s20, s20, s17
	s_sub_i32 s12, s12, s20
	s_sub_i32 s20, s12, s17
	s_cmp_ge_u32 s12, s17
	s_cselect_b32 s12, s20, s12
	s_sub_i32 s20, s12, s17
	s_cmp_ge_u32 s12, s17
	s_cselect_b32 s12, s20, s12
	s_xor_b32 s12, s12, s13
	s_sub_i32 s12, s12, s13
	s_add_i32 s16, s16, s12
	s_and_saveexec_b64 s[12:13], s[6:7]
	v_lshl_add_u32 v48, s16, 8, v4
	v_ashrrev_i32_e32 v49, 31, v48
	v_lshlrev_b64 v[48:49], 6, v[48:49]
	v_lshl_add_u64 v[24:25], s[8:9], 0, v[48:49]
	global_load_dwordx4 v[48:51], v[24:25], off
	global_load_dwordx4 v[52:55], v[24:25], off offset:16
	global_load_dwordx4 v[56:59], v[24:25], off offset:32
	global_load_dwordx4 v[60:63], v[24:25], off offset:48
	s_or_b64 exec, exec, s[12:13]
	s_add_u32 s10, s10, s46
	s_addc_u32 s11, s11, s47
	s_ashr_i32 s12, s10, 31
	s_lshr_b32 s12, s12, 29
	s_add_i32 s12, s10, s12
	s_ashr_i32 s13, s12, 3
	s_and_b32 s12, s12, -8
	s_sub_i32 s12, s10, s12
	s_cmp_lt_i32 s12, 0
	s_cselect_b32 s16, s14, 0x160
	s_mul_i32 s12, s12, s16
	s_add_i32 s12, s12, s13
	s_mul_hi_i32 s13, s12, 0x2e8ba2e9
	s_lshr_b32 s16, s13, 31
	s_ashr_i32 s13, s13, 4
	s_add_i32 s13, s13, s16
	s_lshl_b32 s16, s13, 2
	s_sub_i32 s17, 0x80, s16
	s_min_i32 s17, s17, 4
	s_abs_i32 s17, s17
	v_cvt_f32_u32_e32 v7, s17
	s_sub_i32 s20, 0, s17
	s_mul_i32 s13, s13, 88
	s_sub_i32 s12, s12, s13
	v_rcp_iflag_f32_e32 v7, v7
	s_ashr_i32 s13, s12, 31
	s_abs_i32 s12, s12
	v_mul_f32_e32 v7, 0x4f7ffffe, v7
	v_cvt_u32_f32_e32 v7, v7
	s_nop 0
	v_readfirstlane_b32 s21, v7
	s_mul_i32 s20, s20, s21
	s_mul_hi_u32 s20, s21, s20
	s_add_i32 s21, s21, s20
	s_mul_hi_u32 s20, s12, s21
	s_mul_i32 s20, s20, s17
	s_sub_i32 s12, s12, s20
	s_sub_i32 s20, s12, s17
	s_cmp_ge_u32 s12, s17
	s_cselect_b32 s12, s20, s12
	s_sub_i32 s20, s12, s17
	s_cmp_ge_u32 s12, s17
	s_cselect_b32 s12, s20, s12
	s_xor_b32 s12, s12, s13
	s_sub_i32 s12, s12, s13
	s_add_i32 s16, s16, s12
	s_and_saveexec_b64 s[12:13], s[6:7]
	v_lshl_add_u32 v64, s16, 8, v4
	v_ashrrev_i32_e32 v65, 31, v64
	v_lshlrev_b64 v[64:65], 6, v[64:65]
	v_lshl_add_u64 v[24:25], s[8:9], 0, v[64:65]
	global_load_dwordx4 v[64:67], v[24:25], off
	global_load_dwordx4 v[68:71], v[24:25], off offset:16
	global_load_dwordx4 v[72:75], v[24:25], off offset:32
	global_load_dwordx4 v[76:79], v[24:25], off offset:48
	s_or_b64 exec, exec, s[12:13]
	s_add_u32 s10, s10, s46
	s_addc_u32 s11, s11, s47
	s_ashr_i32 s12, s10, 31
	s_lshr_b32 s12, s12, 29
	s_add_i32 s12, s10, s12
	s_ashr_i32 s13, s12, 3
	s_and_b32 s12, s12, -8
	s_sub_i32 s12, s10, s12
	s_cmp_lt_i32 s12, 0
	s_cselect_b32 s16, s14, 0x160
	s_mul_i32 s12, s12, s16
;     __device__ __forceinline__ bool next(int i, Unit& u) const {
;         const long L = (long)i * G + c; if (L >= nwg) return false;
;         int wgid = (int)L; { const int q = nwg / NXCD, r = nwg % NXCD, xcd = wgid % NXCD, off = wgid / NXCD; wgid = (xcd < r ? xcd * (q + 1) : r * (q + 1) + (xcd - r) * q) + off; }
;         const int nig = WGM * nN, gid = wgid / nig, fm = gid * WGM, gsz = (nM - fm) < WGM ? (nM - fm) : WGM;
;         u.pm = fm + ((wgid % nig) % gsz); u.pn = (wgid % nig) / gsz; u.idx = i; return true;
;     }
; __global__ void __launch_bounds__(512, 2) hybrid_fwd(Args args) {
;     ...
;         { pg8::Unit pu; for (int i = 0; S.next(i, pu); ++i) if (tid < 256) rst[i * 256 + tid] = row_rstd(SSQ + 3 * SSQ_STRIDE, pu.pm * 256 + tid);
	s_add_i32 s12, s12, s13
	s_mul_hi_i32 s13, s12, 0x2e8ba2e9
	s_lshr_b32 s16, s13, 31
	s_ashr_i32 s13, s13, 4
	s_add_i32 s13, s13, s16
	s_lshl_b32 s16, s13, 2
	s_sub_i32 s17, 0x80, s16
	s_min_i32 s17, s17, 4
	s_abs_i32 s17, s17
	v_cvt_f32_u32_e32 v7, s17
	s_sub_i32 s20, 0, s17
	s_mul_i32 s13, s13, 88
	s_sub_i32 s12, s12, s13
	v_rcp_iflag_f32_e32 v7, v7
	s_ashr_i32 s13, s12, 31
	s_abs_i32 s12, s12
	v_mul_f32_e32 v7, 0x4f7ffffe, v7
	v_cvt_u32_f32_e32 v7, v7
	s_nop 0
	v_readfirstlane_b32 s21, v7
	s_mul_i32 s20, s20, s21
	s_mul_hi_u32 s20, s21, s20
	s_add_i32 s21, s21, s20
	s_mul_hi_u32 s20, s12, s21
	s_mul_i32 s20, s20, s17
	s_sub_i32 s12, s12, s20
	s_sub_i32 s20, s12, s17
	s_cmp_ge_u32 s12, s17
	s_cselect_b32 s12, s20, s12
	s_sub_i32 s20, s12, s17
	s_cmp_ge_u32 s12, s17
	s_cselect_b32 s12, s20, s12
	s_xor_b32 s12, s12, s13
	s_sub_i32 s12, s12, s13
	s_add_i32 s16, s16, s12
	s_and_saveexec_b64 s[12:13], s[6:7]
	v_lshl_add_u32 v80, s16, 8, v4
	v_ashrrev_i32_e32 v81, 31, v80
	v_lshlrev_b64 v[80:81], 6, v[80:81]
	v_lshl_add_u64 v[24:25], s[8:9], 0, v[80:81]
	global_load_dwordx4 v[80:83], v[24:25], off
	global_load_dwordx4 v[84:87], v[24:25], off offset:16
	global_load_dwordx4 v[88:91], v[24:25], off offset:32
	global_load_dwordx4 v[92:95], v[24:25], off offset:48
	s_or_b64 exec, exec, s[12:13]
	s_add_u32 s10, s10, s46
	s_addc_u32 s11, s11, s47
	s_ashr_i32 s12, s10, 31
	s_lshr_b32 s12, s12, 29
	s_add_i32 s12, s10, s12
	s_ashr_i32 s13, s12, 3
	s_and_b32 s12, s12, -8
	s_sub_i32 s12, s10, s12
	s_cmp_lt_i32 s12, 0
	s_cselect_b32 s16, s14, 0x160
	s_mul_i32 s12, s12, s16
	s_add_i32 s12, s12, s13
	s_mul_hi_i32 s13, s12, 0x2e8ba2e9
	s_lshr_b32 s16, s13, 31
	s_ashr_i32 s13, s13, 4
	s_add_i32 s13, s13, s16
	s_lshl_b32 s16, s13, 2
	s_sub_i32 s17, 0x80, s16
	s_min_i32 s17, s17, 4
	s_abs_i32 s17, s17
	v_cvt_f32_u32_e32 v7, s17
	s_sub_i32 s20, 0, s17
	s_mul_i32 s13, s13, 88
	s_sub_i32 s12, s12, s13
	v_rcp_iflag_f32_e32 v7, v7
	s_ashr_i32 s13, s12, 31
	s_abs_i32 s12, s12
	v_mul_f32_e32 v7, 0x4f7ffffe, v7
	v_cvt_u32_f32_e32 v7, v7
	s_nop 0
	v_readfirstlane_b32 s21, v7
	s_mul_i32 s20, s20, s21
	s_mul_hi_u32 s20, s21, s20
	s_add_i32 s21, s21, s20
	s_mul_hi_u32 s20, s12, s21
	s_mul_i32 s20, s20, s17
	s_sub_i32 s12, s12, s20
	s_sub_i32 s20, s12, s17
	s_cmp_ge_u32 s12, s17
	s_cselect_b32 s12, s20, s12
	s_sub_i32 s20, s12, s17
	s_cmp_ge_u32 s12, s17
	s_cselect_b32 s12, s20, s12
	s_xor_b32 s12, s12, s13
	s_sub_i32 s12, s12, s13
	s_add_i32 s16, s16, s12
	s_and_saveexec_b64 s[12:13], s[6:7]
	v_lshl_add_u32 v96, s16, 8, v4
	v_ashrrev_i32_e32 v97, 31, v96
	v_lshlrev_b64 v[96:97], 6, v[96:97]
	v_lshl_add_u64 v[24:25], s[8:9], 0, v[96:97]
	global_load_dwordx4 v[96:99], v[24:25], off
	global_load_dwordx4 v[100:103], v[24:25], off offset:16
	global_load_dwordx4 v[104:107], v[24:25], off offset:32
	global_load_dwordx4 v[108:111], v[24:25], off offset:48
	s_or_b64 exec, exec, s[12:13]
	s_add_u32 s10, s10, s46
	s_addc_u32 s11, s11, s47
	s_ashr_i32 s12, s10, 31
	s_lshr_b32 s12, s12, 29
	s_add_i32 s12, s10, s12
	s_ashr_i32 s13, s12, 3
	s_and_b32 s12, s12, -8
	s_sub_i32 s12, s10, s12
	s_cmp_lt_i32 s12, 0
	s_cselect_b32 s16, s14, 0x160
	s_mul_i32 s12, s12, s16
	s_add_i32 s12, s12, s13
	s_mul_hi_i32 s13, s12, 0x2e8ba2e9
	s_lshr_b32 s16, s13, 31
	s_ashr_i32 s13, s13, 4
	s_add_i32 s13, s13, s16
	s_lshl_b32 s16, s13, 2
	s_sub_i32 s17, 0x80, s16
	s_min_i32 s17, s17, 4
	s_abs_i32 s17, s17
	v_cvt_f32_u32_e32 v7, s17
	s_sub_i32 s20, 0, s17
	s_mul_i32 s13, s13, 88
	s_sub_i32 s12, s12, s13
	v_rcp_iflag_f32_e32 v7, v7
	s_ashr_i32 s13, s12, 31
	s_abs_i32 s12, s12
	v_mul_f32_e32 v7, 0x4f7ffffe, v7
	v_cvt_u32_f32_e32 v7, v7
	s_nop 0
	v_readfirstlane_b32 s21, v7
	s_mul_i32 s20, s20, s21
	s_mul_hi_u32 s20, s21, s20
	s_add_i32 s21, s21, s20
	s_mul_hi_u32 s20, s12, s21
	s_mul_i32 s20, s20, s17
	s_sub_i32 s12, s12, s20
	s_sub_i32 s20, s12, s17
	s_cmp_ge_u32 s12, s17
	s_cselect_b32 s12, s20, s12
	s_sub_i32 s20, s12, s17
	s_cmp_ge_u32 s12, s17
	s_cselect_b32 s12, s20, s12
	s_xor_b32 s12, s12, s13
	s_sub_i32 s12, s12, s13
	s_add_i32 s16, s16, s12
	s_and_saveexec_b64 s[12:13], s[6:7]
	v_lshl_add_u32 v112, s16, 8, v4
	v_ashrrev_i32_e32 v113, 31, v112
	v_lshlrev_b64 v[112:113], 6, v[112:113]
	v_lshl_add_u64 v[24:25], s[8:9], 0, v[112:113]
	global_load_dwordx4 v[112:115], v[24:25], off
	global_load_dwordx4 v[116:119], v[24:25], off offset:16
	global_load_dwordx4 v[120:123], v[24:25], off offset:32
	global_load_dwordx4 v[124:127], v[24:25], off offset:48
	s_or_b64 exec, exec, s[12:13]
	s_add_u32 s10, s10, s46
	s_addc_u32 s11, s11, s47
	s_ashr_i32 s12, s10, 31
	s_lshr_b32 s12, s12, 29
	s_add_i32 s12, s10, s12
	s_ashr_i32 s13, s12, 3
	s_and_b32 s12, s12, -8
	s_sub_i32 s12, s10, s12
	s_cmp_lt_i32 s12, 0
	s_cselect_b32 s16, s14, 0x160
	s_mul_i32 s12, s12, s16
	s_add_i32 s12, s12, s13
	s_mul_hi_i32 s13, s12, 0x2e8ba2e9
	s_lshr_b32 s16, s13, 31
	s_ashr_i32 s13, s13, 4
	s_add_i32 s13, s13, s16
	s_lshl_b32 s16, s13, 2
	s_sub_i32 s17, 0x80, s16
	s_min_i32 s17, s17, 4
	s_abs_i32 s17, s17
	v_cvt_f32_u32_e32 v7, s17
	s_sub_i32 s20, 0, s17
	s_mul_i32 s13, s13, 88
	s_sub_i32 s12, s12, s13
	v_rcp_iflag_f32_e32 v7, v7
	s_ashr_i32 s13, s12, 31
	s_abs_i32 s12, s12
	v_mul_f32_e32 v7, 0x4f7ffffe, v7
	v_cvt_u32_f32_e32 v7, v7
	s_nop 0
	v_readfirstlane_b32 s21, v7
	s_mul_i32 s20, s20, s21
	s_mul_hi_u32 s20, s21, s20
	s_add_i32 s21, s21, s20
	s_mul_hi_u32 s20, s12, s21
	s_mul_i32 s20, s20, s17
	s_sub_i32 s12, s12, s20
	s_sub_i32 s20, s12, s17
	s_cmp_ge_u32 s12, s17
	s_cselect_b32 s12, s20, s12
	s_sub_i32 s20, s12, s17
	s_cmp_ge_u32 s12, s17
	s_cselect_b32 s12, s20, s12
	s_xor_b32 s12, s12, s13
	s_sub_i32 s12, s12, s13
;     __device__ __forceinline__ bool next(int i, Unit& u) const {
;         const long L = (long)i * G + c; if (L >= nwg) return false;
;         int wgid = (int)L; { const int q = nwg / NXCD, r = nwg % NXCD, xcd = wgid % NXCD, off = wgid / NXCD; wgid = (xcd < r ? xcd * (q + 1) : r * (q + 1) + (xcd - r) * q) + off; }
;         const int nig = WGM * nN, gid = wgid / nig, fm = gid * WGM, gsz = (nM - fm) < WGM ? (nM - fm) : WGM;
;         u.pm = fm + ((wgid % nig) % gsz); u.pn = (wgid % nig) / gsz; u.idx = i; return true;
;     }
; __global__ void __launch_bounds__(512, 2) hybrid_fwd(Args args) {
;     ...
;         { pg8::Unit pu; for (int i = 0; S.next(i, pu); ++i) if (tid < 256) rst[i * 256 + tid] = row_rstd(SSQ + 3 * SSQ_STRIDE, pu.pm * 256 + tid);
	s_add_i32 s16, s16, s12
	s_and_saveexec_b64 s[12:13], s[6:7]
	v_lshl_add_u32 v128, s16, 8, v4
	v_ashrrev_i32_e32 v129, 31, v128
	v_lshlrev_b64 v[128:129], 6, v[128:129]
	v_lshl_add_u64 v[24:25], s[8:9], 0, v[128:129]
	global_load_dwordx4 v[128:131], v[24:25], off
	global_load_dwordx4 v[132:135], v[24:25], off offset:16
	global_load_dwordx4 v[136:139], v[24:25], off offset:32
	global_load_dwordx4 v[140:143], v[24:25], off offset:48
	s_or_b64 exec, exec, s[12:13]
	s_add_u32 s10, s10, s46
	s_addc_u32 s11, s11, s47
	s_ashr_i32 s12, s10, 31
	s_lshr_b32 s12, s12, 29
	s_add_i32 s12, s10, s12
	s_ashr_i32 s13, s12, 3
	s_and_b32 s12, s12, -8
	s_sub_i32 s12, s10, s12
	s_cmp_lt_i32 s12, 0
	s_cselect_b32 s16, s14, 0x160
	s_mul_i32 s12, s12, s16
	s_add_i32 s12, s12, s13
	s_mul_hi_i32 s13, s12, 0x2e8ba2e9
	s_lshr_b32 s16, s13, 31
	s_ashr_i32 s13, s13, 4
	s_add_i32 s13, s13, s16
	s_lshl_b32 s16, s13, 2
	s_sub_i32 s17, 0x80, s16
	s_min_i32 s17, s17, 4
	s_abs_i32 s17, s17
	v_cvt_f32_u32_e32 v7, s17
	s_sub_i32 s20, 0, s17
	s_mul_i32 s13, s13, 88
	s_sub_i32 s12, s12, s13
	v_rcp_iflag_f32_e32 v7, v7
	s_ashr_i32 s13, s12, 31
	s_abs_i32 s12, s12
	v_mul_f32_e32 v7, 0x4f7ffffe, v7
	v_cvt_u32_f32_e32 v7, v7
	s_nop 0
	v_readfirstlane_b32 s21, v7
	s_mul_i32 s20, s20, s21
	s_mul_hi_u32 s20, s21, s20
	s_add_i32 s21, s21, s20
	s_mul_hi_u32 s20, s12, s21
	s_mul_i32 s20, s20, s17
	s_sub_i32 s12, s12, s20
	s_sub_i32 s20, s12, s17
	s_cmp_ge_u32 s12, s17
	s_cselect_b32 s12, s20, s12
	s_sub_i32 s20, s12, s17
	s_cmp_ge_u32 s12, s17
	s_cselect_b32 s12, s20, s12
	s_xor_b32 s12, s12, s13
	s_sub_i32 s12, s12, s13
	s_add_i32 s16, s16, s12
	s_and_saveexec_b64 s[12:13], s[6:7]
	v_lshl_add_u32 v144, s16, 8, v4
	v_ashrrev_i32_e32 v145, 31, v144
	v_lshlrev_b64 v[144:145], 6, v[144:145]
	v_lshl_add_u64 v[24:25], s[8:9], 0, v[144:145]
	global_load_dwordx4 v[144:147], v[24:25], off
	global_load_dwordx4 v[148:151], v[24:25], off offset:16
	global_load_dwordx4 v[152:155], v[24:25], off offset:32
	global_load_dwordx4 v[156:159], v[24:25], off offset:48
	s_or_b64 exec, exec, s[12:13]
	s_add_u32 s10, s10, s46
	s_addc_u32 s11, s11, s47
	s_ashr_i32 s12, s10, 31
	s_lshr_b32 s12, s12, 29
	s_add_i32 s12, s10, s12
	s_ashr_i32 s13, s12, 3
	s_and_b32 s12, s12, -8
	s_sub_i32 s12, s10, s12
	s_cmp_lt_i32 s12, 0
	s_cselect_b32 s16, s14, 0x160
	s_mul_i32 s12, s12, s16
	s_add_i32 s12, s12, s13
	s_mul_hi_i32 s13, s12, 0x2e8ba2e9
	s_lshr_b32 s16, s13, 31
	s_ashr_i32 s13, s13, 4
	s_add_i32 s13, s13, s16
	s_lshl_b32 s16, s13, 2
	s_sub_i32 s17, 0x80, s16
	s_min_i32 s17, s17, 4
	s_abs_i32 s17, s17
	v_cvt_f32_u32_e32 v7, s17
	s_sub_i32 s20, 0, s17
	s_mul_i32 s13, s13, 88
	s_sub_i32 s12, s12, s13
	v_rcp_iflag_f32_e32 v7, v7
	s_ashr_i32 s13, s12, 31
	s_abs_i32 s12, s12
	v_mul_f32_e32 v7, 0x4f7ffffe, v7
	v_cvt_u32_f32_e32 v7, v7
	s_nop 0
	v_readfirstlane_b32 s21, v7
	s_mul_i32 s20, s20, s21
	s_mul_hi_u32 s20, s21, s20
	s_add_i32 s21, s21, s20
	s_mul_hi_u32 s20, s12, s21
	s_mul_i32 s20, s20, s17
	s_sub_i32 s12, s12, s20
	s_sub_i32 s20, s12, s17
	s_cmp_ge_u32 s12, s17
	s_cselect_b32 s12, s20, s12
	s_sub_i32 s20, s12, s17
	s_cmp_ge_u32 s12, s17
	s_cselect_b32 s12, s20, s12
	s_xor_b32 s12, s12, s13
	s_sub_i32 s12, s12, s13
	s_add_i32 s16, s16, s12
	s_and_saveexec_b64 s[12:13], s[6:7]
	v_lshl_add_u32 v160, s16, 8, v4
	v_ashrrev_i32_e32 v161, 31, v160
	v_lshlrev_b64 v[160:161], 6, v[160:161]
	v_lshl_add_u64 v[24:25], s[8:9], 0, v[160:161]
	global_load_dwordx4 v[160:163], v[24:25], off
	global_load_dwordx4 v[164:167], v[24:25], off offset:16
	global_load_dwordx4 v[168:171], v[24:25], off offset:32
	global_load_dwordx4 v[172:175], v[24:25], off offset:48
	s_or_b64 exec, exec, s[12:13]
	s_add_u32 s10, s10, s46
	s_addc_u32 s11, s11, s47
	s_ashr_i32 s12, s10, 31
	s_lshr_b32 s12, s12, 29
	s_add_i32 s12, s10, s12
	s_ashr_i32 s13, s12, 3
	s_and_b32 s12, s12, -8
	s_sub_i32 s12, s10, s12
	s_cmp_lt_i32 s12, 0
	s_cselect_b32 s16, s14, 0x160
	s_mul_i32 s12, s12, s16
	s_add_i32 s12, s12, s13
	s_mul_hi_i32 s13, s12, 0x2e8ba2e9
	s_lshr_b32 s16, s13, 31
	s_ashr_i32 s13, s13, 4
	s_add_i32 s13, s13, s16
	s_lshl_b32 s16, s13, 2
	s_sub_i32 s17, 0x80, s16
	s_min_i32 s17, s17, 4
	s_abs_i32 s17, s17
	v_cvt_f32_u32_e32 v7, s17
	s_sub_i32 s20, 0, s17
	s_mul_i32 s13, s13, 88
	s_sub_i32 s12, s12, s13
	v_rcp_iflag_f32_e32 v7, v7
	s_ashr_i32 s13, s12, 31
	s_abs_i32 s12, s12
	v_mul_f32_e32 v7, 0x4f7ffffe, v7
	v_cvt_u32_f32_e32 v7, v7
	s_nop 0
	v_readfirstlane_b32 s21, v7
	s_mul_i32 s20, s20, s21
	s_mul_hi_u32 s20, s21, s20
	s_add_i32 s21, s21, s20
	s_mul_hi_u32 s20, s12, s21
	s_mul_i32 s20, s20, s17
	s_sub_i32 s12, s12, s20
	s_sub_i32 s20, s12, s17
	s_cmp_ge_u32 s12, s17
	s_cselect_b32 s12, s20, s12
	s_sub_i32 s20, s12, s17
	s_cmp_ge_u32 s12, s17
	s_cselect_b32 s12, s20, s12
	s_xor_b32 s12, s12, s13
	s_sub_i32 s12, s12, s13
	s_add_i32 s16, s16, s12
	s_and_saveexec_b64 s[12:13], s[6:7]
	v_lshl_add_u32 v176, s16, 8, v4
	v_ashrrev_i32_e32 v177, 31, v176
	v_lshlrev_b64 v[176:177], 6, v[176:177]
	v_lshl_add_u64 v[24:25], s[8:9], 0, v[176:177]
	global_load_dwordx4 v[176:179], v[24:25], off
	global_load_dwordx4 v[180:183], v[24:25], off offset:16
	global_load_dwordx4 v[184:187], v[24:25], off offset:32
	global_load_dwordx4 v[188:191], v[24:25], off offset:48
	s_or_b64 exec, exec, s[12:13]
	s_add_u32 s10, s10, s46
	s_addc_u32 s11, s11, s47
	s_ashr_i32 s12, s10, 31
	s_lshr_b32 s12, s12, 29
	s_add_i32 s12, s10, s12
	s_ashr_i32 s13, s12, 3
	s_and_b32 s12, s12, -8
	s_sub_i32 s12, s10, s12
	s_cmp_lt_i32 s12, 0
	s_cselect_b32 s16, s14, 0x160
	s_mul_i32 s12, s12, s16
	s_add_i32 s12, s12, s13
	s_mul_hi_i32 s13, s12, 0x2e8ba2e9
	s_lshr_b32 s16, s13, 31
	s_ashr_i32 s13, s13, 4
	s_add_i32 s13, s13, s16
	s_lshl_b32 s16, s13, 2
	s_sub_i32 s17, 0x80, s16
	s_min_i32 s17, s17, 4
	s_abs_i32 s17, s17
	v_cvt_f32_u32_e32 v7, s17
	s_sub_i32 s20, 0, s17
	s_mul_i32 s13, s13, 88
	s_sub_i32 s12, s12, s13
	v_rcp_iflag_f32_e32 v7, v7
	s_ashr_i32 s13, s12, 31
	s_abs_i32 s12, s12
	v_mul_f32_e32 v7, 0x4f7ffffe, v7
	v_cvt_u32_f32_e32 v7, v7
	s_nop 0
	v_readfirstlane_b32 s21, v7
	s_mul_i32 s20, s20, s21
	s_mul_hi_u32 s20, s21, s20
	s_add_i32 s21, s21, s20
	s_mul_hi_u32 s20, s12, s21
	s_mul_i32 s20, s20, s17
	s_sub_i32 s12, s12, s20
	s_sub_i32 s20, s12, s17
	s_cmp_ge_u32 s12, s17
	s_cselect_b32 s12, s20, s12
	s_sub_i32 s20, s12, s17
	s_cmp_ge_u32 s12, s17
	s_cselect_b32 s12, s20, s12
	s_xor_b32 s12, s12, s13
	s_sub_i32 s12, s12, s13
	s_add_i32 s16, s16, s12
	s_and_saveexec_b64 s[12:13], s[6:7]
	v_lshl_add_u32 v192, s16, 8, v4
	v_ashrrev_i32_e32 v193, 31, v192
	v_lshlrev_b64 v[192:193], 6, v[192:193]
	v_lshl_add_u64 v[24:25], s[8:9], 0, v[192:193]
	global_load_dwordx4 v[192:195], v[24:25], off
	global_load_dwordx4 v[196:199], v[24:25], off offset:16
	global_load_dwordx4 v[200:203], v[24:25], off offset:32
	global_load_dwordx4 v[204:207], v[24:25], off offset:48
	s_or_b64 exec, exec, s[12:13]
	s_and_saveexec_b64 s[12:13], s[6:7]
	s_waitcnt vmcnt(0)
; __device__ __forceinline__ float row_rstd(const float* ssq, int row) {
;     const f32x4* p = (const f32x4*)(ssq + (size_t)row * 16);
;     const f32x4 a = p[0], b = p[1], c = p[2], d = p[3];
;     const float s = ((a[0] + a[1]) + (a[2] + a[3])) + ((b[0] + b[1]) + (b[2] + b[3])) + ((c[0] + c[1]) + (c[2] + c[3])) + ((d[0] + d[1]) + (d[2] + d[3]));
;     return rsqrtf(s * (1.0f / 1024.0f) + EPS);
; __global__ void __launch_bounds__(512, 2) hybrid_fwd(Args args) {
;     ...
;         { pg8::Unit pu; for (int i = 0; S.next(i, pu); ++i) if (tid < 256) rst[i * 256 + tid] = row_rstd(SSQ + 3 * SSQ_STRIDE, pu.pm * 256 + tid);
	v_mov_b32_e32 v24, v33
	v_mov_b32_e32 v25, v34
	v_mov_b32_e32 v33, v35
	v_mov_b32_e32 v34, v37
	v_mov_b32_e32 v35, v38
	v_mov_b32_e32 v37, v39
	v_pk_add_f32 v[32:33], v[24:25], v[32:33]
	v_pk_add_f32 v[34:35], v[34:35], v[36:37]
	v_pk_add_f32 v[32:33], v[32:33], v[32:33] op_sel:[0,1] op_sel_hi:[1,0]
	v_pk_add_f32 v[34:35], v[34:35], v[34:35] op_sel:[0,1] op_sel_hi:[1,0]
	v_add_f32_e32 v38, v40, v41
	v_add_f32_e32 v40, v42, v43
	v_mov_b32_e32 v39, v46
	v_mov_b32_e32 v41, v47
	v_mov_b32_e32 v33, v44
	v_mov_b32_e32 v35, v45
	v_pk_add_f32 v[36:37], v[38:39], v[40:41]
	v_pk_add_f32 v[32:33], v[32:33], v[34:35]
	s_nop 0
	v_pk_add_f32 v[32:33], v[32:33], v[36:37]
	s_nop 0
	v_add_f32_e32 v7, v32, v33
	v_fmamk_f32 v7, v7, 0x3a800000, v6
	v_mul_f32_e32 v32, 0x4b800000, v7
	v_cmp_gt_f32_e32 vcc, s15, v7
	s_nop 1
	v_cndmask_b32_e32 v7, v7, v32, vcc
	v_rsq_f32_e32 v7, v7
	s_nop 0
	v_mul_f32_e32 v32, 0x45800000, v7
	v_cndmask_b32_e32 v7, v7, v32, vcc
	ds_write_b32 v5, v7
	v_mov_b32_e32 v24, v49
	v_mov_b32_e32 v25, v50
	v_mov_b32_e32 v49, v51
	v_mov_b32_e32 v50, v53
	v_mov_b32_e32 v51, v54
	v_mov_b32_e32 v53, v55
	v_pk_add_f32 v[48:49], v[24:25], v[48:49]
	v_pk_add_f32 v[50:51], v[50:51], v[52:53]
	v_pk_add_f32 v[48:49], v[48:49], v[48:49] op_sel:[0,1] op_sel_hi:[1,0]
	v_pk_add_f32 v[50:51], v[50:51], v[50:51] op_sel:[0,1] op_sel_hi:[1,0]
	v_add_f32_e32 v54, v56, v57
	v_add_f32_e32 v56, v58, v59
	v_mov_b32_e32 v55, v62
	v_mov_b32_e32 v57, v63
	v_mov_b32_e32 v49, v60
	v_mov_b32_e32 v51, v61
	v_pk_add_f32 v[52:53], v[54:55], v[56:57]
	v_pk_add_f32 v[48:49], v[48:49], v[50:51]
	s_nop 0
	v_pk_add_f32 v[48:49], v[48:49], v[52:53]
	s_nop 0
	v_add_f32_e32 v7, v48, v49
	v_fmamk_f32 v7, v7, 0x3a800000, v6
	v_mul_f32_e32 v48, 0x4b800000, v7
	v_cmp_gt_f32_e32 vcc, s15, v7
	s_nop 1
	v_cndmask_b32_e32 v7, v7, v48, vcc
	v_rsq_f32_e32 v7, v7
	s_nop 0
	v_mul_f32_e32 v48, 0x45800000, v7
	v_cndmask_b32_e32 v7, v7, v48, vcc
	ds_write_b32 v5, v7 offset:1024
	v_mov_b32_e32 v24, v65
	v_mov_b32_e32 v25, v66
	v_mov_b32_e32 v65, v67
	v_mov_b32_e32 v66, v69
	v_mov_b32_e32 v67, v70
	v_mov_b32_e32 v69, v71
	v_pk_add_f32 v[64:65], v[24:25], v[64:65]
	v_pk_add_f32 v[66:67], v[66:67], v[68:69]
	v_pk_add_f32 v[64:65], v[64:65], v[64:65] op_sel:[0,1] op_sel_hi:[1,0]
	v_pk_add_f32 v[66:67], v[66:67], v[66:67] op_sel:[0,1] op_sel_hi:[1,0]
	v_add_f32_e32 v70, v72, v73
	v_add_f32_e32 v72, v74, v75
	v_mov_b32_e32 v71, v78
	v_mov_b32_e32 v73, v79
	v_mov_b32_e32 v65, v76
	v_mov_b32_e32 v67, v77
	v_pk_add_f32 v[68:69], v[70:71], v[72:73]
	v_pk_add_f32 v[64:65], v[64:65], v[66:67]
	s_nop 0
	v_pk_add_f32 v[64:65], v[64:65], v[68:69]
	s_nop 0
	v_add_f32_e32 v7, v64, v65
	v_fmamk_f32 v7, v7, 0x3a800000, v6
	v_mul_f32_e32 v64, 0x4b800000, v7
	v_cmp_gt_f32_e32 vcc, s15, v7
	s_nop 1
	v_cndmask_b32_e32 v7, v7, v64, vcc
	v_rsq_f32_e32 v7, v7
	s_nop 0
	v_mul_f32_e32 v64, 0x45800000, v7
	v_cndmask_b32_e32 v7, v7, v64, vcc
	ds_write_b32 v5, v7 offset:2048
	v_mov_b32_e32 v24, v81
	v_mov_b32_e32 v25, v82
	v_mov_b32_e32 v81, v83
	v_mov_b32_e32 v82, v85
	v_mov_b32_e32 v83, v86
	v_mov_b32_e32 v85, v87
	v_pk_add_f32 v[80:81], v[24:25], v[80:81]
	v_pk_add_f32 v[82:83], v[82:83], v[84:85]
	v_pk_add_f32 v[80:81], v[80:81], v[80:81] op_sel:[0,1] op_sel_hi:[1,0]
	v_pk_add_f32 v[82:83], v[82:83], v[82:83] op_sel:[0,1] op_sel_hi:[1,0]
	v_add_f32_e32 v86, v88, v89
	v_add_f32_e32 v88, v90, v91
	v_mov_b32_e32 v87, v94
	v_mov_b32_e32 v89, v95
	v_mov_b32_e32 v81, v92
	v_mov_b32_e32 v83, v93
	v_pk_add_f32 v[84:85], v[86:87], v[88:89]
	v_pk_add_f32 v[80:81], v[80:81], v[82:83]
	s_nop 0
	v_pk_add_f32 v[80:81], v[80:81], v[84:85]
	s_nop 0
	v_add_f32_e32 v7, v80, v81
	v_fmamk_f32 v7, v7, 0x3a800000, v6
	v_mul_f32_e32 v80, 0x4b800000, v7
	v_cmp_gt_f32_e32 vcc, s15, v7
	s_nop 1
	v_cndmask_b32_e32 v7, v7, v80, vcc
	v_rsq_f32_e32 v7, v7
	s_nop 0
	v_mul_f32_e32 v80, 0x45800000, v7
	v_cndmask_b32_e32 v7, v7, v80, vcc
	ds_write_b32 v5, v7 offset:3072
	v_mov_b32_e32 v24, v97
	v_mov_b32_e32 v25, v98
	v_mov_b32_e32 v97, v99
	v_mov_b32_e32 v98, v101
	v_mov_b32_e32 v99, v102
	v_mov_b32_e32 v101, v103
	v_pk_add_f32 v[96:97], v[24:25], v[96:97]
	v_pk_add_f32 v[98:99], v[98:99], v[100:101]
	v_pk_add_f32 v[96:97], v[96:97], v[96:97] op_sel:[0,1] op_sel_hi:[1,0]
	v_pk_add_f32 v[98:99], v[98:99], v[98:99] op_sel:[0,1] op_sel_hi:[1,0]
	v_add_f32_e32 v102, v104, v105
	v_add_f32_e32 v104, v106, v107
	v_mov_b32_e32 v103, v110
	v_mov_b32_e32 v105, v111
	v_mov_b32_e32 v97, v108
	v_mov_b32_e32 v99, v109
	v_pk_add_f32 v[100:101], v[102:103], v[104:105]
	v_pk_add_f32 v[96:97], v[96:97], v[98:99]
	s_nop 0
	v_pk_add_f32 v[96:97], v[96:97], v[100:101]
	s_nop 0
	v_add_f32_e32 v7, v96, v97
	v_fmamk_f32 v7, v7, 0x3a800000, v6
	v_mul_f32_e32 v96, 0x4b800000, v7
	v_cmp_gt_f32_e32 vcc, s15, v7
	s_nop 1
	v_cndmask_b32_e32 v7, v7, v96, vcc
	v_rsq_f32_e32 v7, v7
	s_nop 0
	v_mul_f32_e32 v96, 0x45800000, v7
	v_cndmask_b32_e32 v7, v7, v96, vcc
	ds_write_b32 v5, v7 offset:4096
	v_mov_b32_e32 v24, v113
	v_mov_b32_e32 v25, v114
	v_mov_b32_e32 v113, v115
	v_mov_b32_e32 v114, v117
	v_mov_b32_e32 v115, v118
	v_mov_b32_e32 v117, v119
	v_pk_add_f32 v[112:113], v[24:25], v[112:113]
	v_pk_add_f32 v[114:115], v[114:115], v[116:117]
	v_pk_add_f32 v[112:113], v[112:113], v[112:113] op_sel:[0,1] op_sel_hi:[1,0]
	v_pk_add_f32 v[114:115], v[114:115], v[114:115] op_sel:[0,1] op_sel_hi:[1,0]
	v_add_f32_e32 v118, v120, v121
	v_add_f32_e32 v120, v122, v123
	v_mov_b32_e32 v119, v126
	v_mov_b32_e32 v121, v127
	v_mov_b32_e32 v113, v124
	v_mov_b32_e32 v115, v125
	v_pk_add_f32 v[116:117], v[118:119], v[120:121]
	v_pk_add_f32 v[112:113], v[112:113], v[114:115]
	s_nop 0
; __device__ __forceinline__ float row_rstd(const float* ssq, int row) {
;     const f32x4* p = (const f32x4*)(ssq + (size_t)row * 16);
;     const f32x4 a = p[0], b = p[1], c = p[2], d = p[3];
;     const float s = ((a[0] + a[1]) + (a[2] + a[3])) + ((b[0] + b[1]) + (b[2] + b[3])) + ((c[0] + c[1]) + (c[2] + c[3])) + ((d[0] + d[1]) + (d[2] + d[3]));
;     return rsqrtf(s * (1.0f / 1024.0f) + EPS);
; __global__ void __launch_bounds__(512, 2) hybrid_fwd(Args args) {
;     ...
;         { pg8::Unit pu; for (int i = 0; S.next(i, pu); ++i) if (tid < 256) rst[i * 256 + tid] = row_rstd(SSQ + 3 * SSQ_STRIDE, pu.pm * 256 + tid);
	v_pk_add_f32 v[112:113], v[112:113], v[116:117]
	s_nop 0
	v_add_f32_e32 v7, v112, v113
	v_fmamk_f32 v7, v7, 0x3a800000, v6
	v_mul_f32_e32 v112, 0x4b800000, v7
	v_cmp_gt_f32_e32 vcc, s15, v7
	s_nop 1
	v_cndmask_b32_e32 v7, v7, v112, vcc
	v_rsq_f32_e32 v7, v7
	s_nop 0
	v_mul_f32_e32 v112, 0x45800000, v7
	v_cndmask_b32_e32 v7, v7, v112, vcc
	ds_write_b32 v5, v7 offset:5120
	v_mov_b32_e32 v24, v129
	v_mov_b32_e32 v25, v130
	v_mov_b32_e32 v129, v131
	v_mov_b32_e32 v130, v133
	v_mov_b32_e32 v131, v134
	v_mov_b32_e32 v133, v135
	v_pk_add_f32 v[128:129], v[24:25], v[128:129]
	v_pk_add_f32 v[130:131], v[130:131], v[132:133]
	v_pk_add_f32 v[128:129], v[128:129], v[128:129] op_sel:[0,1] op_sel_hi:[1,0]
	v_pk_add_f32 v[130:131], v[130:131], v[130:131] op_sel:[0,1] op_sel_hi:[1,0]
	v_add_f32_e32 v134, v136, v137
	v_add_f32_e32 v136, v138, v139
	v_mov_b32_e32 v135, v142
	v_mov_b32_e32 v137, v143
	v_mov_b32_e32 v129, v140
	v_mov_b32_e32 v131, v141
	v_pk_add_f32 v[132:133], v[134:135], v[136:137]
	v_pk_add_f32 v[128:129], v[128:129], v[130:131]
	s_nop 0
	v_pk_add_f32 v[128:129], v[128:129], v[132:133]
	s_nop 0
	v_add_f32_e32 v7, v128, v129
	v_fmamk_f32 v7, v7, 0x3a800000, v6
	v_mul_f32_e32 v128, 0x4b800000, v7
	v_cmp_gt_f32_e32 vcc, s15, v7
	s_nop 1
	v_cndmask_b32_e32 v7, v7, v128, vcc
	v_rsq_f32_e32 v7, v7
	s_nop 0
	v_mul_f32_e32 v128, 0x45800000, v7
	v_cndmask_b32_e32 v7, v7, v128, vcc
	ds_write_b32 v5, v7 offset:6144
	v_mov_b32_e32 v24, v145
	v_mov_b32_e32 v25, v146
	v_mov_b32_e32 v145, v147
	v_mov_b32_e32 v146, v149
	v_mov_b32_e32 v147, v150
	v_mov_b32_e32 v149, v151
	v_pk_add_f32 v[144:145], v[24:25], v[144:145]
	v_pk_add_f32 v[146:147], v[146:147], v[148:149]
	v_pk_add_f32 v[144:145], v[144:145], v[144:145] op_sel:[0,1] op_sel_hi:[1,0]
	v_pk_add_f32 v[146:147], v[146:147], v[146:147] op_sel:[0,1] op_sel_hi:[1,0]
	v_add_f32_e32 v150, v152, v153
	v_add_f32_e32 v152, v154, v155
	v_mov_b32_e32 v151, v158
	v_mov_b32_e32 v153, v159
	v_mov_b32_e32 v145, v156
	v_mov_b32_e32 v147, v157
	v_pk_add_f32 v[148:149], v[150:151], v[152:153]
	v_pk_add_f32 v[144:145], v[144:145], v[146:147]
	s_nop 0
	v_pk_add_f32 v[144:145], v[144:145], v[148:149]
	s_nop 0
	v_add_f32_e32 v7, v144, v145
	v_fmamk_f32 v7, v7, 0x3a800000, v6
	v_mul_f32_e32 v144, 0x4b800000, v7
	v_cmp_gt_f32_e32 vcc, s15, v7
	s_nop 1
	v_cndmask_b32_e32 v7, v7, v144, vcc
	v_rsq_f32_e32 v7, v7
	s_nop 0
	v_mul_f32_e32 v144, 0x45800000, v7
	v_cndmask_b32_e32 v7, v7, v144, vcc
	ds_write_b32 v5, v7 offset:7168
	v_mov_b32_e32 v24, v161
	v_mov_b32_e32 v25, v162
	v_mov_b32_e32 v161, v163
	v_mov_b32_e32 v162, v165
	v_mov_b32_e32 v163, v166
	v_mov_b32_e32 v165, v167
	v_pk_add_f32 v[160:161], v[24:25], v[160:161]
	v_pk_add_f32 v[162:163], v[162:163], v[164:165]
	v_pk_add_f32 v[160:161], v[160:161], v[160:161] op_sel:[0,1] op_sel_hi:[1,0]
	v_pk_add_f32 v[162:163], v[162:163], v[162:163] op_sel:[0,1] op_sel_hi:[1,0]
	v_add_f32_e32 v166, v168, v169
	v_add_f32_e32 v168, v170, v171
	v_mov_b32_e32 v167, v174
	v_mov_b32_e32 v169, v175
	v_mov_b32_e32 v161, v172
	v_mov_b32_e32 v163, v173
	v_pk_add_f32 v[164:165], v[166:167], v[168:169]
	v_pk_add_f32 v[160:161], v[160:161], v[162:163]
	s_nop 0
	v_pk_add_f32 v[160:161], v[160:161], v[164:165]
	s_nop 0
	v_add_f32_e32 v7, v160, v161
	v_fmamk_f32 v7, v7, 0x3a800000, v6
	v_mul_f32_e32 v160, 0x4b800000, v7
	v_cmp_gt_f32_e32 vcc, s15, v7
	s_nop 1
	v_cndmask_b32_e32 v7, v7, v160, vcc
	v_rsq_f32_e32 v7, v7
	s_nop 0
	v_mul_f32_e32 v160, 0x45800000, v7
	v_cndmask_b32_e32 v7, v7, v160, vcc
	ds_write_b32 v5, v7 offset:8192
	v_mov_b32_e32 v24, v177
	v_mov_b32_e32 v25, v178
	v_mov_b32_e32 v177, v179
	v_mov_b32_e32 v178, v181
	v_mov_b32_e32 v179, v182
	v_mov_b32_e32 v181, v183
	v_pk_add_f32 v[176:177], v[24:25], v[176:177]
	v_pk_add_f32 v[178:179], v[178:179], v[180:181]
	v_pk_add_f32 v[176:177], v[176:177], v[176:177] op_sel:[0,1] op_sel_hi:[1,0]
	v_pk_add_f32 v[178:179], v[178:179], v[178:179] op_sel:[0,1] op_sel_hi:[1,0]
	v_add_f32_e32 v182, v184, v185
	v_add_f32_e32 v184, v186, v187
	v_mov_b32_e32 v183, v190
	v_mov_b32_e32 v185, v191
	v_mov_b32_e32 v177, v188
	v_mov_b32_e32 v179, v189
	v_pk_add_f32 v[180:181], v[182:183], v[184:185]
	v_pk_add_f32 v[176:177], v[176:177], v[178:179]
	s_nop 0
	v_pk_add_f32 v[176:177], v[176:177], v[180:181]
	s_nop 0
	v_add_f32_e32 v7, v176, v177
	v_fmamk_f32 v7, v7, 0x3a800000, v6
	v_mul_f32_e32 v176, 0x4b800000, v7
	v_cmp_gt_f32_e32 vcc, s15, v7
	s_nop 1
	v_cndmask_b32_e32 v7, v7, v176, vcc
	v_rsq_f32_e32 v7, v7
	s_nop 0
	v_mul_f32_e32 v176, 0x45800000, v7
	v_cndmask_b32_e32 v7, v7, v176, vcc
	ds_write_b32 v5, v7 offset:9216
	v_mov_b32_e32 v24, v193
	v_mov_b32_e32 v25, v194
	v_mov_b32_e32 v193, v195
	v_mov_b32_e32 v194, v197
	v_mov_b32_e32 v195, v198
	v_mov_b32_e32 v197, v199
	v_pk_add_f32 v[192:193], v[24:25], v[192:193]
	v_pk_add_f32 v[194:195], v[194:195], v[196:197]
	v_pk_add_f32 v[192:193], v[192:193], v[192:193] op_sel:[0,1] op_sel_hi:[1,0]
	v_pk_add_f32 v[194:195], v[194:195], v[194:195] op_sel:[0,1] op_sel_hi:[1,0]
	v_add_f32_e32 v198, v200, v201
	v_add_f32_e32 v200, v202, v203
	v_mov_b32_e32 v199, v206
	v_mov_b32_e32 v201, v207
	v_mov_b32_e32 v193, v204
	v_mov_b32_e32 v195, v205
	v_pk_add_f32 v[196:197], v[198:199], v[200:201]
	v_pk_add_f32 v[192:193], v[192:193], v[194:195]
	s_nop 0
	v_pk_add_f32 v[192:193], v[192:193], v[196:197]
	s_nop 0
	v_add_f32_e32 v7, v192, v193
	v_fmamk_f32 v7, v7, 0x3a800000, v6
	v_mul_f32_e32 v192, 0x4b800000, v7
	v_cmp_gt_f32_e32 vcc, s15, v7
	s_nop 1
	v_cndmask_b32_e32 v7, v7, v192, vcc
	v_rsq_f32_e32 v7, v7
	s_nop 0
	v_mul_f32_e32 v192, 0x45800000, v7
	v_cndmask_b32_e32 v7, v7, v192, vcc
	ds_write_b32 v5, v7 offset:10240
	s_or_b64 exec, exec, s[12:13]
	s_branch .LBB0_1267

;     __device__ __forceinline__ bool next(int i, Unit& u) const {
;         const long L = (long)i * G + c; if (L >= nwg) return false;
;         int wgid = (int)L; { const int q = nwg / NXCD, r = nwg % NXCD, xcd = wgid % NXCD, off = wgid / NXCD; wgid = (xcd < r ? xcd * (q + 1) : r * (q + 1) + (xcd - r) * q) + off; }
;         const int nig = WGM * nN, gid = wgid / nig, fm = gid * WGM, gsz = (nM - fm) < WGM ? (nM - fm) : WGM;
;         u.pm = fm + ((wgid % nig) % gsz); u.pn = (wgid % nig) / gsz; u.idx = i; return true;
;     }
; template <class Epi, bool HALO>
; __device__ __forceinline__ void gemm_phase(LAS unsigned char* lds, const Gemm g, const StaticOrder& S, const Epi& E) {
;     ...
;         const bool has_next = S.next(ui + 1, nxt);
.LBB0_1275:
	s_add_i32 s89, s89, 1
	s_mul_i32 s6, s89, s47
	s_mul_hi_u32 s7, s89, s46
	s_add_i32 s7, s7, s6
	s_mul_i32 s6, s89, s46
	s_add_u32 s12, s6, s2
	s_addc_u32 s13, s7, s3
	v_cmp_gt_i64_e32 vcc, s[12:13], v[192:193]
	v_cmp_lt_i64_e64 s[6:7], s[12:13], v[190:191]
	s_cbranch_vccnz .LBB0_1277
	s_ashr_i32 s13, s12, 31
	s_lshr_b32 s13, s13, 29
	s_add_i32 s13, s12, s13
	s_ashr_i32 s16, s13, 3
	s_and_b32 s13, s13, -8
	s_sub_i32 s12, s12, s13
	s_cmp_lt_i32 s12, 0
	s_cselect_b32 s13, s69, 0x160
	s_mul_i32 s12, s12, s13
	s_add_i32 s12, s12, s16
	s_mul_hi_i32 s13, s12, 0x2e8ba2e9
	s_lshr_b32 s16, s13, 31
	s_ashr_i32 s13, s13, 4
	s_add_i32 s13, s13, s16
	s_lshl_b32 s16, s13, 2
	s_sub_i32 s17, 0x80, s16
	s_min_i32 s17, s17, 4
	s_abs_i32 s30, s17
	v_cvt_f32_u32_e32 v0, s30
	s_sub_i32 s34, 0, s30
	s_mul_i32 s13, s13, 88
	s_sub_i32 s12, s12, s13
	v_rcp_iflag_f32_e32 v0, v0
	s_abs_i32 s13, s12
	s_xor_b32 s31, s12, s17
	s_ashr_i32 s31, s31, 31
	v_mul_f32_e32 v0, 0x4f7ffffe, v0
	v_cvt_u32_f32_e32 v0, v0
	s_mov_b32 s90, s89
	v_readfirstlane_b32 s35, v0
	s_mul_i32 s34, s34, s35
	s_mul_hi_u32 s34, s35, s34
	s_add_i32 s35, s35, s34
	s_mul_hi_u32 s34, s13, s35
	s_mul_i32 s35, s34, s30
	s_sub_i32 s13, s13, s35
	s_add_i32 s36, s34, 1
	s_sub_i32 s35, s13, s30
	s_cmp_ge_u32 s13, s30
	s_cselect_b32 s34, s36, s34
	s_cselect_b32 s13, s35, s13
	s_add_i32 s35, s34, 1
	s_cmp_ge_u32 s13, s30
	s_cselect_b32 s13, s35, s34
	s_xor_b32 s13, s13, s31
	s_sub_i32 s30, s13, s31
	s_mul_i32 s13, s30, s17
	s_sub_i32 s12, s12, s13
	s_add_i32 s34, s16, s12
